# nt streaming policy on the Wo/FF2 residual epilogues' x tile loads (once-read per phase)
# baseline (speedup 1.0000x reference)
; __device__ __forceinline__ unsigned pk2(float lo, float hi) { unsigned r; asm volatile("v_cvt_pk_bf16_f32 %0, %1, %2" : "=v"(r) : "v"(lo), "v"(hi)); return r; }
;     __device__ __forceinline__ void operator()(const f32x4 (&acc)[2][2][4][2], const Unit& u, int wr, int wc, int fr, int fq) const {
;         const int row0 = u.pm * 256 + wr * 64 + fr, col0 = u.pn * 256 + wc * 32 + 4 * fq;
;         const float* xo = (u.pm < 64) ? xoldA : (xoldB - (size_t)T_P * DM);
; #pragma unroll
;         for (int ai = 0; ai < 2; ++ai)
; #pragma unroll
;             for (int m = 0; m < 4; ++m) {
;                 const int row = row0 + ai * 128 + m * 16; const size_t ro = (size_t)row * DM + col0;
;                 float s = 0.f;
; #pragma unroll
;                 for (int bj = 0; bj < 2; ++bj)
; #pragma unroll
;                     for (int n = 0; n < 2; ++n) {
;                         const size_t o = ro + bj * 128 + n * 16;
;                         const f32x4 xn = *(const f32x4*)(xo + o) + acc[ai][bj][m][n];
;                         *(f32x4*)(xf + o) = xn;
;                         u32x2 w; w.x = pk2(xn[0], xn[1]); w.y = pk2(xn[2], xn[3]); *(u32x2*)(xb + o) = w;
;                         s += (xn[0] * xn[0] + xn[1] * xn[1]) + (xn[2] * xn[2] + xn[3] * xn[3]);
;                     }
;                 s += __shfl_xor(s, 16); s += __shfl_xor(s, 32);
;                 if (fq == 0) ssq[(size_t)row * 16 + u.pn * 4 + wc] = s;
;             }
;     }
.LBB0_781:
	v_lshl_add_u32 v146, s83, 8, v148
	v_lshl_or_b32 v142, s56, 8, v150
	v_ashrrev_i32_e32 v147, 31, v146
	v_ashrrev_i32_e32 v143, 31, v142
	v_lshlrev_b64 v[154:155], 10, v[146:147]
	s_cmp_lt_i32 s83, 64
	v_lshl_add_u64 v[158:159], v[154:155], 0, v[142:143]
	s_cselect_b32 s17, s23, -1
	s_cselect_b32 s16, s22, 0xfc000000
	v_lshlrev_b64 v[160:161], 2, v[158:159]
	v_lshl_add_u64 v[162:163], s[16:17], 0, v[160:161]
	v_subrev_u32_e32 v172, s16, v162
	v_add_u32_e32 v173, 0x0, v172
	global_load_dwordx4 v[174:177], v173, s[16:17] nt
	v_add_u32_e32 v173, 0x40, v172
	global_load_dwordx4 v[178:181], v173, s[16:17] nt
	v_add_u32_e32 v173, 0x200, v172
	global_load_dwordx4 v[182:185], v173, s[16:17] nt
	v_add_u32_e32 v173, 0x240, v172
	global_load_dwordx4 v[186:189], v173, s[16:17] nt
	v_add_u32_e32 v173, 0x10000, v172
	global_load_dwordx4 v[190:193], v173, s[16:17] nt
	v_add_u32_e32 v173, 0x10040, v172
	global_load_dwordx4 v[194:197], v173, s[16:17] nt
	v_add_u32_e32 v173, 0x10200, v172
	global_load_dwordx4 v[198:201], v173, s[16:17] nt
	v_add_u32_e32 v173, 0x10240, v172
	global_load_dwordx4 v[202:205], v173, s[16:17] nt
	v_add_u32_e32 v173, 0x20000, v172
	global_load_dwordx4 v[206:209], v173, s[16:17] nt
	v_add_u32_e32 v173, 0x20040, v172
	global_load_dwordx4 v[210:213], v173, s[16:17] nt
	v_add_u32_e32 v173, 0x20200, v172
	global_load_dwordx4 v[214:217], v173, s[16:17] nt
	v_add_u32_e32 v173, 0x20240, v172
	global_load_dwordx4 v[218:221], v173, s[16:17] nt
	v_add_u32_e32 v173, 0x30000, v172
	global_load_dwordx4 v[232:235], v173, s[16:17] nt
	v_add_u32_e32 v173, 0x30040, v172
	global_load_dwordx4 v[236:239], v173, s[16:17] nt
	v_add_u32_e32 v173, 0x30200, v172
	global_load_dwordx4 v[240:243], v173, s[16:17] nt
	v_add_u32_e32 v173, 0x30240, v172
	global_load_dwordx4 v[244:247], v173, s[16:17] nt
	v_add_u32_e32 v173, 0x80000, v172
	global_load_dwordx4 v[248:251], v173, s[16:17] nt
	v_add_u32_e32 v173, 0x80040, v172
	global_load_dwordx4 v[252:255], v173, s[16:17] nt
	v_lshl_add_u64 v[164:165], v[158:159], 1, s[24:25]
	v_lshl_add_u64 v[170:171], s[28:29], 0, v[160:161]
	v_xor_b32_e32 v153, 32, v152
	s_lshl_b32 s56, s56, 2
	s_ashr_i32 s57, s56, 31
	s_waitcnt vmcnt(17)
	v_mov_b64_e32 v[154:155], v[174:175]
	v_mov_b64_e32 v[156:157], v[176:177]
	v_add_u32_e32 v173, 0x80200, v172
	global_load_dwordx4 v[174:177], v173, s[16:17] nt
	v_pk_add_f32 v[126:127], v[126:127], v[156:157]
	v_pk_add_f32 v[124:125], v[124:125], v[154:155]
	global_store_dwordx4 v[170:171], v[124:127], off
	v_cvt_pk_bf16_f32 v154, v124, v125
	v_cvt_pk_bf16_f32 v155, v126, v127
	global_store_dwordx2 v[164:165], v[154:155], off
	s_waitcnt vmcnt(19)
	v_mov_b64_e32 v[154:155], v[178:179]
	v_mov_b64_e32 v[156:157], v[180:181]
	v_add_u32_e32 v173, 0x80240, v172
	global_load_dwordx4 v[178:181], v173, s[16:17] nt
	v_pk_add_f32 v[122:123], v[122:123], v[156:157]
	v_pk_add_f32 v[120:121], v[120:121], v[154:155]
	global_store_dwordx4 v[170:171], v[120:123], off offset:64
	v_cvt_pk_bf16_f32 v154, v120, v121
	v_cvt_pk_bf16_f32 v155, v122, v123
	global_store_dwordx2 v[164:165], v[154:155], off offset:32
	s_waitcnt vmcnt(21)
	v_mov_b64_e32 v[154:155], v[182:183]
	v_mov_b64_e32 v[156:157], v[184:185]
	v_add_u32_e32 v173, 0x90000, v172
	global_load_dwordx4 v[182:185], v173, s[16:17] nt
	v_pk_add_f32 v[156:157], v[118:119], v[156:157]
	v_pk_add_f32 v[154:155], v[116:117], v[154:155]
	global_store_dwordx4 v[170:171], v[154:157], off offset:512
	v_cvt_pk_bf16_f32 v116, v154, v155
	v_cvt_pk_bf16_f32 v117, v156, v157
	global_store_dwordx2 v[164:165], v[116:117], off offset:256
	v_mul_f32_e32 v118, v125, v125
	v_mul_f32_e32 v119, v127, v127
	v_fmac_f32_e32 v118, v124, v124
	v_fmac_f32_e32 v119, v126, v126
	v_add_f32_e32 v118, v118, v119
	v_mul_f32_e32 v119, v121, v121
	v_mul_f32_e32 v121, v123, v123
	v_fmac_f32_e32 v119, v120, v120
	v_fmac_f32_e32 v121, v122, v122
	v_add_f32_e32 v119, v119, v121
	v_add_f32_e32 v118, v118, v119
	v_mul_f32_e32 v119, v155, v155
	v_mul_f32_e32 v120, v157, v157
	v_fmac_f32_e32 v119, v154, v154
	v_fmac_f32_e32 v120, v156, v156
	v_add_f32_e32 v119, v119, v120
	v_and_b32_e32 v117, 64, v152
	v_add_f32_e32 v122, v118, v119
	v_xor_b32_e32 v116, 16, v152
	v_add_u32_e32 v117, 64, v117
	v_cmp_lt_i32_e32 vcc, v116, v117
	s_waitcnt vmcnt(23)
	v_mov_b64_e32 v[158:159], v[186:187]
	v_mov_b64_e32 v[160:161], v[188:189]
	v_add_u32_e32 v173, 0x90040, v172
	global_load_dwordx4 v[186:189], v173, s[16:17] nt
	v_pk_add_f32 v[120:121], v[114:115], v[160:161]
	v_pk_add_f32 v[118:119], v[112:113], v[158:159]
	v_mul_f32_e32 v113, v121, v121
	v_mul_f32_e32 v112, v119, v119
	v_fmac_f32_e32 v112, v118, v118
	v_fmac_f32_e32 v113, v120, v120
	v_cndmask_b32_e32 v116, v152, v116, vcc
	v_add_f32_e32 v112, v112, v113
	v_lshlrev_b32_e32 v116, 2, v116
	v_add_f32_e32 v112, v122, v112
	ds_bpermute_b32 v113, v116, v112
	v_cmp_lt_i32_e32 vcc, v153, v117
	global_store_dwordx4 v[170:171], v[118:121], off offset:576
	s_waitcnt lgkmcnt(0)
	v_add_f32_e32 v112, v112, v113
	v_cndmask_b32_e32 v114, v152, v153, vcc
	v_lshlrev_b32_e32 v114, 2, v114
	ds_bpermute_b32 v113, v114, v112
	v_cvt_pk_bf16_f32 v118, v118, v119
	v_cvt_pk_bf16_f32 v119, v120, v121
	global_store_dwordx2 v[164:165], v[118:119], off offset:288
	s_and_saveexec_b64 s[58:59], s[12:13]
	s_cbranch_execz .LBB0_783
	s_waitcnt lgkmcnt(0)
	v_add_f32_e32 v115, v112, v113
	v_lshlrev_b64 v[112:113], 6, v[146:147]
	v_lshl_add_u64 v[112:113], s[26:27], 0, v[112:113]
	v_lshl_add_u64 v[112:113], s[56:57], 2, v[112:113]
	s_lshl_b32 s36, s74, 2
	v_lshl_add_u64 v[112:113], v[112:113], 0, s[36:37]
	global_store_dword v[112:113], v115, off
; __device__ __forceinline__ unsigned pk2(float lo, float hi) { unsigned r; asm volatile("v_cvt_pk_bf16_f32 %0, %1, %2" : "=v"(r) : "v"(lo), "v"(hi)); return r; }
;     __device__ __forceinline__ void operator()(const f32x4 (&acc)[2][2][4][2], const Unit& u, int wr, int wc, int fr, int fq) const {
;     ...
;         for (int ai = 0; ai < 2; ++ai)
; #pragma unroll
;             for (int m = 0; m < 4; ++m) {
;                 const int row = row0 + ai * 128 + m * 16; const size_t ro = (size_t)row * DM + col0;
;                 float s = 0.f;
; #pragma unroll
;                 for (int bj = 0; bj < 2; ++bj)
; #pragma unroll
;                     for (int n = 0; n < 2; ++n) {
;                         const size_t o = ro + bj * 128 + n * 16;
;                         const f32x4 xn = *(const f32x4*)(xo + o) + acc[ai][bj][m][n];
;                         *(f32x4*)(xf + o) = xn;
;                         u32x2 w; w.x = pk2(xn[0], xn[1]); w.y = pk2(xn[2], xn[3]); *(u32x2*)(xb + o) = w;
;                         s += (xn[0] * xn[0] + xn[1] * xn[1]) + (xn[2] * xn[2] + xn[3] * xn[3]);
;                     }
;                 s += __shfl_xor(s, 16); s += __shfl_xor(s, 32);
;                 if (fq == 0) ssq[(size_t)row * 16 + u.pn * 4 + wc] = s;
;             }
.LBB0_783:
	s_or_b64 exec, exec, s[58:59]
	v_or_b32_e32 v112, 16, v146
	s_waitcnt lgkmcnt(0)
	v_ashrrev_i32_e32 v113, 31, v112
	v_lshlrev_b64 v[118:119], 10, v[112:113]
	v_lshl_add_u64 v[122:123], v[118:119], 0, v[142:143]
	v_lshlrev_b64 v[124:125], 2, v[122:123]
	v_lshl_add_u64 v[126:127], s[16:17], 0, v[124:125]
	v_lshl_add_u64 v[122:123], v[122:123], 1, s[24:25]
	v_lshl_add_u64 v[124:125], s[28:29], 0, v[124:125]
	s_waitcnt vmcnt(25)
	v_mov_b64_e32 v[118:119], v[190:191]
	v_mov_b64_e32 v[120:121], v[192:193]
	v_add_u32_e32 v173, 0x90200, v172
	global_load_dwordx4 v[190:193], v173, s[16:17] nt
	v_pk_add_f32 v[110:111], v[110:111], v[120:121]
	v_pk_add_f32 v[108:109], v[108:109], v[118:119]
	global_store_dwordx4 v[124:125], v[108:111], off
	v_cvt_pk_bf16_f32 v118, v108, v109
	v_cvt_pk_bf16_f32 v119, v110, v111
	global_store_dwordx2 v[122:123], v[118:119], off
	v_mul_f32_e32 v109, v109, v109
	v_mul_f32_e32 v111, v111, v111
	v_fmac_f32_e32 v109, v108, v108
	v_fmac_f32_e32 v111, v110, v110
	v_add_f32_e32 v108, v109, v111
	s_waitcnt vmcnt(27)
	v_mov_b64_e32 v[118:119], v[194:195]
	v_mov_b64_e32 v[120:121], v[196:197]
	v_add_u32_e32 v173, 0x90240, v172
	global_load_dwordx4 v[194:197], v173, s[16:17] nt
	v_pk_add_f32 v[106:107], v[106:107], v[120:121]
	v_pk_add_f32 v[104:105], v[104:105], v[118:119]
	global_store_dwordx4 v[124:125], v[104:107], off offset:64
	v_cvt_pk_bf16_f32 v118, v104, v105
	v_cvt_pk_bf16_f32 v119, v106, v107
	global_store_dwordx2 v[122:123], v[118:119], off offset:32
	v_mul_f32_e32 v105, v105, v105
	v_mul_f32_e32 v107, v107, v107
	v_fmac_f32_e32 v105, v104, v104
	v_fmac_f32_e32 v107, v106, v106
	v_add_f32_e32 v104, v105, v107
	v_add_f32_e32 v104, v108, v104
	s_waitcnt vmcnt(29)
	v_mov_b64_e32 v[118:119], v[198:199]
	v_mov_b64_e32 v[120:121], v[200:201]
	v_add_u32_e32 v173, 0xa0000, v172
	global_load_dwordx4 v[198:201], v173, s[16:17] nt
	v_pk_add_f32 v[102:103], v[102:103], v[120:121]
	v_pk_add_f32 v[100:101], v[100:101], v[118:119]
	global_store_dwordx4 v[124:125], v[100:103], off offset:512
	v_cvt_pk_bf16_f32 v118, v100, v101
	v_cvt_pk_bf16_f32 v119, v102, v103
	global_store_dwordx2 v[122:123], v[118:119], off offset:256
	v_mul_f32_e32 v101, v101, v101
	v_mul_f32_e32 v103, v103, v103
	v_fmac_f32_e32 v101, v100, v100
	v_fmac_f32_e32 v103, v102, v102
	v_add_f32_e32 v100, v101, v103
	v_add_f32_e32 v102, v104, v100
	s_waitcnt vmcnt(31)
	v_mov_b64_e32 v[118:119], v[202:203]
	v_mov_b64_e32 v[120:121], v[204:205]
	v_add_u32_e32 v173, 0xa0040, v172
	global_load_dwordx4 v[202:205], v173, s[16:17] nt
	v_pk_add_f32 v[100:101], v[98:99], v[120:121]
	v_pk_add_f32 v[98:99], v[96:97], v[118:119]
	v_mul_f32_e32 v97, v101, v101
	v_mul_f32_e32 v96, v99, v99
	v_fmac_f32_e32 v96, v98, v98
	v_fmac_f32_e32 v97, v100, v100
	v_add_f32_e32 v96, v96, v97
	v_add_f32_e32 v96, v102, v96
	ds_bpermute_b32 v97, v116, v96
	global_store_dwordx4 v[124:125], v[98:101], off offset:576
	s_waitcnt lgkmcnt(0)
	v_add_f32_e32 v96, v96, v97
	ds_bpermute_b32 v97, v114, v96
	v_cvt_pk_bf16_f32 v98, v98, v99
	v_cvt_pk_bf16_f32 v99, v100, v101
	global_store_dwordx2 v[122:123], v[98:99], off offset:288
	s_and_saveexec_b64 s[58:59], s[12:13]
	s_cbranch_execz .LBB0_785
	s_waitcnt lgkmcnt(0)
	v_add_f32_e32 v98, v96, v97
	v_lshlrev_b64 v[96:97], 6, v[112:113]
	v_lshl_add_u64 v[96:97], s[26:27], 0, v[96:97]
	v_lshl_add_u64 v[96:97], s[56:57], 2, v[96:97]
	s_lshl_b32 s36, s74, 2
	v_lshl_add_u64 v[96:97], v[96:97], 0, s[36:37]
	global_store_dword v[96:97], v98, off
; __device__ __forceinline__ unsigned pk2(float lo, float hi) { unsigned r; asm volatile("v_cvt_pk_bf16_f32 %0, %1, %2" : "=v"(r) : "v"(lo), "v"(hi)); return r; }
;     __device__ __forceinline__ void operator()(const f32x4 (&acc)[2][2][4][2], const Unit& u, int wr, int wc, int fr, int fq) const {
;     ...
;         for (int ai = 0; ai < 2; ++ai)
; #pragma unroll
;             for (int m = 0; m < 4; ++m) {
;                 const int row = row0 + ai * 128 + m * 16; const size_t ro = (size_t)row * DM + col0;
;                 float s = 0.f;
; #pragma unroll
;                 for (int bj = 0; bj < 2; ++bj)
; #pragma unroll
;                     for (int n = 0; n < 2; ++n) {
;                         const size_t o = ro + bj * 128 + n * 16;
;                         const f32x4 xn = *(const f32x4*)(xo + o) + acc[ai][bj][m][n];
;                         *(f32x4*)(xf + o) = xn;
;                         u32x2 w; w.x = pk2(xn[0], xn[1]); w.y = pk2(xn[2], xn[3]); *(u32x2*)(xb + o) = w;
;                         s += (xn[0] * xn[0] + xn[1] * xn[1]) + (xn[2] * xn[2] + xn[3] * xn[3]);
;                     }
;                 s += __shfl_xor(s, 16); s += __shfl_xor(s, 32);
;                 if (fq == 0) ssq[(size_t)row * 16 + u.pn * 4 + wc] = s;
;             }
.LBB0_785:
	s_or_b64 exec, exec, s[58:59]
	v_or_b32_e32 v96, 32, v146
	s_waitcnt lgkmcnt(0)
	v_ashrrev_i32_e32 v97, 31, v96
	v_lshlrev_b64 v[98:99], 10, v[96:97]
	v_lshl_add_u64 v[102:103], v[98:99], 0, v[142:143]
	v_lshlrev_b64 v[104:105], 2, v[102:103]
	v_lshl_add_u64 v[106:107], s[16:17], 0, v[104:105]
	v_lshl_add_u64 v[102:103], v[102:103], 1, s[24:25]
	v_lshl_add_u64 v[104:105], s[28:29], 0, v[104:105]
	s_waitcnt vmcnt(33)
	v_mov_b64_e32 v[98:99], v[206:207]
	v_mov_b64_e32 v[100:101], v[208:209]
	v_add_u32_e32 v173, 0xa0200, v172
	global_load_dwordx4 v[206:209], v173, s[16:17] nt
	v_pk_add_f32 v[94:95], v[94:95], v[100:101]
	v_pk_add_f32 v[92:93], v[92:93], v[98:99]
	global_store_dwordx4 v[104:105], v[92:95], off
	v_cvt_pk_bf16_f32 v98, v92, v93
	v_cvt_pk_bf16_f32 v99, v94, v95
	global_store_dwordx2 v[102:103], v[98:99], off
	v_mul_f32_e32 v93, v93, v93
	v_mul_f32_e32 v95, v95, v95
	v_fmac_f32_e32 v93, v92, v92
	v_fmac_f32_e32 v95, v94, v94
	v_add_f32_e32 v92, v93, v95
	s_waitcnt vmcnt(35)
	v_mov_b64_e32 v[98:99], v[210:211]
	v_mov_b64_e32 v[100:101], v[212:213]
	v_add_u32_e32 v173, 0xa0240, v172
	global_load_dwordx4 v[210:213], v173, s[16:17] nt
	v_pk_add_f32 v[90:91], v[90:91], v[100:101]
	v_pk_add_f32 v[88:89], v[88:89], v[98:99]
	global_store_dwordx4 v[104:105], v[88:91], off offset:64
	v_cvt_pk_bf16_f32 v98, v88, v89
	v_cvt_pk_bf16_f32 v99, v90, v91
	global_store_dwordx2 v[102:103], v[98:99], off offset:32
	v_mul_f32_e32 v89, v89, v89
	v_mul_f32_e32 v91, v91, v91
	v_fmac_f32_e32 v89, v88, v88
	v_fmac_f32_e32 v91, v90, v90
	v_add_f32_e32 v88, v89, v91
	v_add_f32_e32 v88, v92, v88
	s_waitcnt vmcnt(37)
	v_mov_b64_e32 v[98:99], v[214:215]
	v_mov_b64_e32 v[100:101], v[216:217]
	v_add_u32_e32 v173, 0xb0000, v172
	global_load_dwordx4 v[214:217], v173, s[16:17] nt
	v_pk_add_f32 v[86:87], v[86:87], v[100:101]
	v_pk_add_f32 v[84:85], v[84:85], v[98:99]
	global_store_dwordx4 v[104:105], v[84:87], off offset:512
	v_cvt_pk_bf16_f32 v98, v84, v85
	v_cvt_pk_bf16_f32 v99, v86, v87
	global_store_dwordx2 v[102:103], v[98:99], off offset:256
	v_mul_f32_e32 v85, v85, v85
	v_mul_f32_e32 v87, v87, v87
	v_fmac_f32_e32 v85, v84, v84
	v_fmac_f32_e32 v87, v86, v86
	v_add_f32_e32 v84, v85, v87
	v_add_f32_e32 v86, v88, v84
	s_waitcnt vmcnt(39)
	v_mov_b64_e32 v[98:99], v[218:219]
	v_mov_b64_e32 v[100:101], v[220:221]
	v_add_u32_e32 v173, 0xb0040, v172
	global_load_dwordx4 v[218:221], v173, s[16:17] nt
	v_pk_add_f32 v[84:85], v[82:83], v[100:101]
	v_pk_add_f32 v[82:83], v[80:81], v[98:99]
	v_mul_f32_e32 v81, v85, v85
	v_mul_f32_e32 v80, v83, v83
	v_fmac_f32_e32 v80, v82, v82
	v_fmac_f32_e32 v81, v84, v84
	v_add_f32_e32 v80, v80, v81
	v_add_f32_e32 v80, v86, v80
	ds_bpermute_b32 v81, v116, v80
	global_store_dwordx4 v[104:105], v[82:85], off offset:576
	s_waitcnt lgkmcnt(0)
	v_add_f32_e32 v80, v80, v81
	ds_bpermute_b32 v81, v114, v80
	v_cvt_pk_bf16_f32 v82, v82, v83
	v_cvt_pk_bf16_f32 v83, v84, v85
	global_store_dwordx2 v[102:103], v[82:83], off offset:288
	s_and_saveexec_b64 s[58:59], s[12:13]
	s_cbranch_execz .LBB0_787
	s_waitcnt lgkmcnt(0)
	v_add_f32_e32 v82, v80, v81
	v_lshlrev_b64 v[80:81], 6, v[96:97]
	v_lshl_add_u64 v[80:81], s[26:27], 0, v[80:81]
	v_lshl_add_u64 v[80:81], s[56:57], 2, v[80:81]
	s_lshl_b32 s36, s74, 2
	v_lshl_add_u64 v[80:81], v[80:81], 0, s[36:37]
	global_store_dword v[80:81], v82, off
.LBB0_787:
	s_or_b64 exec, exec, s[58:59]
	v_or_b32_e32 v80, 48, v146
	s_waitcnt lgkmcnt(0)
	v_ashrrev_i32_e32 v81, 31, v80
	v_lshlrev_b64 v[82:83], 10, v[80:81]
	v_lshl_add_u64 v[86:87], v[82:83], 0, v[142:143]
	v_lshlrev_b64 v[88:89], 2, v[86:87]
	v_lshl_add_u64 v[90:91], s[16:17], 0, v[88:89]
	v_lshl_add_u64 v[86:87], v[86:87], 1, s[24:25]
	v_lshl_add_u64 v[88:89], s[28:29], 0, v[88:89]
	s_waitcnt vmcnt(41)
	v_mov_b64_e32 v[82:83], v[232:233]
	v_mov_b64_e32 v[84:85], v[234:235]
	v_add_u32_e32 v173, 0xb0200, v172
	global_load_dwordx4 v[232:235], v173, s[16:17] nt
	v_pk_add_f32 v[78:79], v[78:79], v[84:85]
	v_pk_add_f32 v[76:77], v[76:77], v[82:83]
	global_store_dwordx4 v[88:89], v[76:79], off
	v_cvt_pk_bf16_f32 v82, v76, v77
	v_cvt_pk_bf16_f32 v83, v78, v79
	global_store_dwordx2 v[86:87], v[82:83], off
	v_mul_f32_e32 v77, v77, v77
	v_mul_f32_e32 v79, v79, v79
	v_fmac_f32_e32 v77, v76, v76
	v_fmac_f32_e32 v79, v78, v78
	v_add_f32_e32 v76, v77, v79
	s_waitcnt vmcnt(43)
	v_mov_b64_e32 v[82:83], v[236:237]
	v_mov_b64_e32 v[84:85], v[238:239]
	v_add_u32_e32 v173, 0xb0240, v172
	global_load_dwordx4 v[236:239], v173, s[16:17] nt
	v_pk_add_f32 v[74:75], v[74:75], v[84:85]
	v_pk_add_f32 v[72:73], v[72:73], v[82:83]
	global_store_dwordx4 v[88:89], v[72:75], off offset:64
	v_cvt_pk_bf16_f32 v82, v72, v73
	v_cvt_pk_bf16_f32 v83, v74, v75
	global_store_dwordx2 v[86:87], v[82:83], off offset:32
	v_mul_f32_e32 v73, v73, v73
	v_mul_f32_e32 v75, v75, v75
	v_fmac_f32_e32 v73, v72, v72
	v_fmac_f32_e32 v75, v74, v74
	v_add_f32_e32 v72, v73, v75
	v_add_f32_e32 v72, v76, v72
	s_waitcnt vmcnt(45)
	v_mov_b64_e32 v[82:83], v[240:241]
	v_mov_b64_e32 v[84:85], v[242:243]
	v_pk_add_f32 v[70:71], v[70:71], v[84:85]
	v_pk_add_f32 v[68:69], v[68:69], v[82:83]
	global_store_dwordx4 v[88:89], v[68:71], off offset:512
	v_cvt_pk_bf16_f32 v82, v68, v69
	v_cvt_pk_bf16_f32 v83, v70, v71
	global_store_dwordx2 v[86:87], v[82:83], off offset:256
	v_mul_f32_e32 v69, v69, v69
	v_mul_f32_e32 v71, v71, v71
	v_fmac_f32_e32 v69, v68, v68
	v_fmac_f32_e32 v71, v70, v70
	v_add_f32_e32 v68, v69, v71
	v_add_f32_e32 v70, v72, v68
	s_waitcnt vmcnt(46)
	v_mov_b64_e32 v[82:83], v[244:245]
	v_mov_b64_e32 v[84:85], v[246:247]
	v_pk_add_f32 v[68:69], v[66:67], v[84:85]
	v_pk_add_f32 v[66:67], v[64:65], v[82:83]
	v_mul_f32_e32 v65, v69, v69
	v_mul_f32_e32 v64, v67, v67
	v_fmac_f32_e32 v64, v66, v66
	v_fmac_f32_e32 v65, v68, v68
	v_add_f32_e32 v64, v64, v65
	v_add_f32_e32 v64, v70, v64
	ds_bpermute_b32 v65, v116, v64
	global_store_dwordx4 v[88:89], v[66:69], off offset:576
	s_waitcnt lgkmcnt(0)
	v_add_f32_e32 v64, v64, v65
	ds_bpermute_b32 v65, v114, v64
	v_cvt_pk_bf16_f32 v66, v66, v67
	v_cvt_pk_bf16_f32 v67, v68, v69
	global_store_dwordx2 v[86:87], v[66:67], off offset:288
	s_and_saveexec_b64 s[58:59], s[12:13]
	s_cbranch_execz .LBB0_789
	s_waitcnt lgkmcnt(0)
	v_add_f32_e32 v66, v64, v65
	v_lshlrev_b64 v[64:65], 6, v[80:81]
	v_lshl_add_u64 v[64:65], s[26:27], 0, v[64:65]
	v_lshl_add_u64 v[64:65], s[56:57], 2, v[64:65]
	s_lshl_b32 s36, s74, 2
	v_lshl_add_u64 v[64:65], v[64:65], 0, s[36:37]
	global_store_dword v[64:65], v66, off

; __device__ __forceinline__ unsigned pk2(float lo, float hi) { unsigned r; asm volatile("v_cvt_pk_bf16_f32 %0, %1, %2" : "=v"(r) : "v"(lo), "v"(hi)); return r; }
;     __device__ __forceinline__ void operator()(const f32x4 (&acc)[2][2][4][2], const Unit& u, int wr, int wc, int fr, int fq) const {
;         const int row0 = u.pm * 256 + wr * 64 + fr, col0 = u.pn * 256 + wc * 32 + 4 * fq;
;         const float* xo = (u.pm < 64) ? xoldA : (xoldB - (size_t)T_P * DM);
; #pragma unroll
;         for (int ai = 0; ai < 2; ++ai)
; #pragma unroll
;             for (int m = 0; m < 4; ++m) {
;                 const int row = row0 + ai * 128 + m * 16; const size_t ro = (size_t)row * DM + col0;
;                 float s = 0.f;
; #pragma unroll
;                 for (int bj = 0; bj < 2; ++bj)
; #pragma unroll
;                     for (int n = 0; n < 2; ++n) {
;                         const size_t o = ro + bj * 128 + n * 16;
;                         const f32x4 xn = *(const f32x4*)(xo + o) + acc[ai][bj][m][n];
;                         *(f32x4*)(xf + o) = xn;
;                         u32x2 w; w.x = pk2(xn[0], xn[1]); w.y = pk2(xn[2], xn[3]); *(u32x2*)(xb + o) = w;
;                         s += (xn[0] * xn[0] + xn[1] * xn[1]) + (xn[2] * xn[2] + xn[3] * xn[3]);
;                     }
;                 s += __shfl_xor(s, 16); s += __shfl_xor(s, 32);
;                 if (fq == 0) ssq[(size_t)row * 16 + u.pn * 4 + wc] = s;
;             }
;     }
.LBB0_1037:
	v_lshl_add_u32 v138, s58, 8, v140
	v_lshl_or_b32 v136, s56, 8, v142
	v_ashrrev_i32_e32 v139, 31, v138
	v_ashrrev_i32_e32 v137, 31, v136
	v_lshlrev_b64 v[148:149], 10, v[138:139]
	s_cmp_lt_i32 s58, 64
	v_lshl_add_u64 v[152:153], v[148:149], 0, v[136:137]
	s_cselect_b32 s17, s21, -1
	s_cselect_b32 s16, s20, 0xfc000000
	v_lshlrev_b64 v[154:155], 2, v[152:153]
	v_lshl_add_u64 v[156:157], s[16:17], 0, v[154:155]
	v_subrev_u32_e32 v162, s16, v156
	v_add_u32_e32 v163, 0x0, v162
	global_load_dwordx4 v[170:173], v163, s[16:17] nt
	v_add_u32_e32 v163, 0x40, v162
	global_load_dwordx4 v[174:177], v163, s[16:17] nt
	v_add_u32_e32 v163, 0x200, v162
	global_load_dwordx4 v[178:181], v163, s[16:17] nt
	v_add_u32_e32 v163, 0x240, v162
	global_load_dwordx4 v[182:185], v163, s[16:17] nt
	v_add_u32_e32 v163, 0x10000, v162
	global_load_dwordx4 v[186:189], v163, s[16:17] nt
	v_add_u32_e32 v163, 0x10040, v162
	global_load_dwordx4 v[190:193], v163, s[16:17] nt
	v_add_u32_e32 v163, 0x10200, v162
	global_load_dwordx4 v[194:197], v163, s[16:17] nt
	v_add_u32_e32 v163, 0x10240, v162
	global_load_dwordx4 v[198:201], v163, s[16:17] nt
	v_add_u32_e32 v163, 0x20000, v162
	global_load_dwordx4 v[202:205], v163, s[16:17] nt
	v_add_u32_e32 v163, 0x20040, v162
	global_load_dwordx4 v[206:209], v163, s[16:17] nt
	v_add_u32_e32 v163, 0x20200, v162
	global_load_dwordx4 v[210:213], v163, s[16:17] nt
	v_add_u32_e32 v163, 0x20240, v162
	global_load_dwordx4 v[232:235], v163, s[16:17] nt
	v_add_u32_e32 v163, 0x30000, v162
	global_load_dwordx4 v[236:239], v163, s[16:17] nt
	v_add_u32_e32 v163, 0x30040, v162
	global_load_dwordx4 v[240:243], v163, s[16:17] nt
	v_add_u32_e32 v163, 0x30200, v162
	global_load_dwordx4 v[244:247], v163, s[16:17] nt
	v_add_u32_e32 v163, 0x30240, v162
	global_load_dwordx4 v[248:251], v163, s[16:17] nt
	v_add_u32_e32 v163, 0x80000, v162
	global_load_dwordx4 v[252:255], v163, s[16:17] nt
	v_lshl_add_u64 v[158:159], v[152:153], 1, s[26:27]
	v_lshl_add_u64 v[160:161], s[20:21], 0, v[154:155]
	v_xor_b32_e32 v147, 32, v146
	s_lshl_b32 s56, s56, 2
	s_ashr_i32 s57, s56, 31
	s_waitcnt vmcnt(16)
	v_mov_b64_e32 v[148:149], v[170:171]
	v_mov_b64_e32 v[150:151], v[172:173]
	v_add_u32_e32 v163, 0x80040, v162
	global_load_dwordx4 v[170:173], v163, s[16:17] nt
	v_pk_add_f32 v[126:127], v[126:127], v[150:151]
	v_pk_add_f32 v[124:125], v[124:125], v[148:149]
	global_store_dwordx4 v[160:161], v[124:127], off
	v_cvt_pk_bf16_f32 v148, v124, v125
	v_cvt_pk_bf16_f32 v149, v126, v127
	global_store_dwordx2 v[158:159], v[148:149], off
	s_waitcnt vmcnt(18)
	v_mov_b64_e32 v[148:149], v[174:175]
	v_mov_b64_e32 v[150:151], v[176:177]
	v_add_u32_e32 v163, 0x80200, v162
	global_load_dwordx4 v[174:177], v163, s[16:17] nt
	v_pk_add_f32 v[122:123], v[122:123], v[150:151]
	v_pk_add_f32 v[120:121], v[120:121], v[148:149]
	global_store_dwordx4 v[160:161], v[120:123], off offset:64
	v_cvt_pk_bf16_f32 v148, v120, v121
	v_cvt_pk_bf16_f32 v149, v122, v123
	global_store_dwordx2 v[158:159], v[148:149], off offset:32
	s_waitcnt vmcnt(20)
	v_mov_b64_e32 v[148:149], v[178:179]
	v_mov_b64_e32 v[150:151], v[180:181]
	v_add_u32_e32 v163, 0x80240, v162
	global_load_dwordx4 v[178:181], v163, s[16:17] nt
	v_pk_add_f32 v[150:151], v[118:119], v[150:151]
	v_pk_add_f32 v[148:149], v[116:117], v[148:149]
	global_store_dwordx4 v[160:161], v[148:151], off offset:512
	v_cvt_pk_bf16_f32 v116, v148, v149
	v_cvt_pk_bf16_f32 v117, v150, v151
	global_store_dwordx2 v[158:159], v[116:117], off offset:256
	v_mul_f32_e32 v118, v125, v125
	v_mul_f32_e32 v119, v127, v127
	v_fmac_f32_e32 v118, v124, v124
	v_fmac_f32_e32 v119, v126, v126
	v_add_f32_e32 v118, v118, v119
	v_mul_f32_e32 v119, v121, v121
	v_mul_f32_e32 v121, v123, v123
	v_fmac_f32_e32 v119, v120, v120
	v_fmac_f32_e32 v121, v122, v122
	v_add_f32_e32 v119, v119, v121
	v_add_f32_e32 v118, v118, v119
	v_mul_f32_e32 v119, v149, v149
	v_mul_f32_e32 v120, v151, v151
	v_fmac_f32_e32 v119, v148, v148
	v_fmac_f32_e32 v120, v150, v150
	v_add_f32_e32 v119, v119, v120
	v_and_b32_e32 v117, 64, v146
	v_add_f32_e32 v122, v118, v119
	v_xor_b32_e32 v116, 16, v146
	v_add_u32_e32 v117, 64, v117
	v_cmp_lt_i32_e32 vcc, v116, v117
	s_waitcnt vmcnt(22)
	v_mov_b64_e32 v[152:153], v[182:183]
	v_mov_b64_e32 v[154:155], v[184:185]
	v_add_u32_e32 v163, 0x90000, v162
	global_load_dwordx4 v[182:185], v163, s[16:17] nt
	v_pk_add_f32 v[120:121], v[114:115], v[154:155]
	v_pk_add_f32 v[118:119], v[112:113], v[152:153]
	v_mul_f32_e32 v113, v121, v121
	v_mul_f32_e32 v112, v119, v119
	v_fmac_f32_e32 v112, v118, v118
	v_fmac_f32_e32 v113, v120, v120
	v_cndmask_b32_e32 v116, v146, v116, vcc
	v_add_f32_e32 v112, v112, v113
	v_lshlrev_b32_e32 v116, 2, v116
	v_add_f32_e32 v112, v122, v112
	ds_bpermute_b32 v113, v116, v112
	v_cmp_lt_i32_e32 vcc, v147, v117
	global_store_dwordx4 v[160:161], v[118:121], off offset:576
	s_waitcnt lgkmcnt(0)
	v_add_f32_e32 v112, v112, v113
	v_cndmask_b32_e32 v114, v146, v147, vcc
	v_lshlrev_b32_e32 v114, 2, v114
	ds_bpermute_b32 v113, v114, v112
	v_cvt_pk_bf16_f32 v118, v118, v119
	v_cvt_pk_bf16_f32 v119, v120, v121
	global_store_dwordx2 v[158:159], v[118:119], off offset:288
	s_and_saveexec_b64 s[58:59], s[12:13]
	s_cbranch_execz .LBB0_1039
	s_waitcnt lgkmcnt(0)
	v_add_f32_e32 v115, v112, v113
	v_lshlrev_b64 v[112:113], 6, v[138:139]
	v_lshl_add_u64 v[112:113], s[28:29], 0, v[112:113]
	v_lshl_add_u64 v[112:113], s[56:57], 2, v[112:113]
	s_lshl_b32 s30, s84, 2
	v_lshl_add_u64 v[112:113], v[112:113], 0, s[30:31]
	global_store_dword v[112:113], v115, off
; __device__ __forceinline__ unsigned pk2(float lo, float hi) { unsigned r; asm volatile("v_cvt_pk_bf16_f32 %0, %1, %2" : "=v"(r) : "v"(lo), "v"(hi)); return r; }
;     __device__ __forceinline__ void operator()(const f32x4 (&acc)[2][2][4][2], const Unit& u, int wr, int wc, int fr, int fq) const {
;     ...
;         for (int ai = 0; ai < 2; ++ai)
; #pragma unroll
;             for (int m = 0; m < 4; ++m) {
;                 const int row = row0 + ai * 128 + m * 16; const size_t ro = (size_t)row * DM + col0;
;                 float s = 0.f;
; #pragma unroll
;                 for (int bj = 0; bj < 2; ++bj)
; #pragma unroll
;                     for (int n = 0; n < 2; ++n) {
;                         const size_t o = ro + bj * 128 + n * 16;
;                         const f32x4 xn = *(const f32x4*)(xo + o) + acc[ai][bj][m][n];
;                         *(f32x4*)(xf + o) = xn;
;                         u32x2 w; w.x = pk2(xn[0], xn[1]); w.y = pk2(xn[2], xn[3]); *(u32x2*)(xb + o) = w;
;                         s += (xn[0] * xn[0] + xn[1] * xn[1]) + (xn[2] * xn[2] + xn[3] * xn[3]);
;                     }
;                 s += __shfl_xor(s, 16); s += __shfl_xor(s, 32);
;                 if (fq == 0) ssq[(size_t)row * 16 + u.pn * 4 + wc] = s;
;             }
.LBB0_1039:
	s_or_b64 exec, exec, s[58:59]
	v_or_b32_e32 v112, 16, v138
	s_waitcnt lgkmcnt(0)
	v_ashrrev_i32_e32 v113, 31, v112
	v_lshlrev_b64 v[118:119], 10, v[112:113]
	v_lshl_add_u64 v[122:123], v[118:119], 0, v[136:137]
	v_lshlrev_b64 v[124:125], 2, v[122:123]
	v_lshl_add_u64 v[126:127], s[16:17], 0, v[124:125]
	v_lshl_add_u64 v[122:123], v[122:123], 1, s[26:27]
	v_lshl_add_u64 v[124:125], s[20:21], 0, v[124:125]
	s_waitcnt vmcnt(24)
	v_mov_b64_e32 v[118:119], v[186:187]
	v_mov_b64_e32 v[120:121], v[188:189]
	v_add_u32_e32 v163, 0x90040, v162
	global_load_dwordx4 v[186:189], v163, s[16:17] nt
	v_pk_add_f32 v[110:111], v[110:111], v[120:121]
	v_pk_add_f32 v[108:109], v[108:109], v[118:119]
	global_store_dwordx4 v[124:125], v[108:111], off
	v_cvt_pk_bf16_f32 v118, v108, v109
	v_cvt_pk_bf16_f32 v119, v110, v111
	global_store_dwordx2 v[122:123], v[118:119], off
	v_mul_f32_e32 v109, v109, v109
	v_mul_f32_e32 v111, v111, v111
	v_fmac_f32_e32 v109, v108, v108
	v_fmac_f32_e32 v111, v110, v110
	v_add_f32_e32 v108, v109, v111
	s_waitcnt vmcnt(26)
	v_mov_b64_e32 v[118:119], v[190:191]
	v_mov_b64_e32 v[120:121], v[192:193]
	v_add_u32_e32 v163, 0x90200, v162
	global_load_dwordx4 v[190:193], v163, s[16:17] nt
	v_pk_add_f32 v[106:107], v[106:107], v[120:121]
	v_pk_add_f32 v[104:105], v[104:105], v[118:119]
	global_store_dwordx4 v[124:125], v[104:107], off offset:64
	v_cvt_pk_bf16_f32 v118, v104, v105
	v_cvt_pk_bf16_f32 v119, v106, v107
	global_store_dwordx2 v[122:123], v[118:119], off offset:32
	v_mul_f32_e32 v105, v105, v105
	v_mul_f32_e32 v107, v107, v107
	v_fmac_f32_e32 v105, v104, v104
	v_fmac_f32_e32 v107, v106, v106
	v_add_f32_e32 v104, v105, v107
	v_add_f32_e32 v104, v108, v104
	s_waitcnt vmcnt(28)
	v_mov_b64_e32 v[118:119], v[194:195]
	v_mov_b64_e32 v[120:121], v[196:197]
	v_add_u32_e32 v163, 0x90240, v162
	global_load_dwordx4 v[194:197], v163, s[16:17] nt
	v_pk_add_f32 v[102:103], v[102:103], v[120:121]
	v_pk_add_f32 v[100:101], v[100:101], v[118:119]
	global_store_dwordx4 v[124:125], v[100:103], off offset:512
	v_cvt_pk_bf16_f32 v118, v100, v101
	v_cvt_pk_bf16_f32 v119, v102, v103
	global_store_dwordx2 v[122:123], v[118:119], off offset:256
	v_mul_f32_e32 v101, v101, v101
	v_mul_f32_e32 v103, v103, v103
	v_fmac_f32_e32 v101, v100, v100
	v_fmac_f32_e32 v103, v102, v102
	v_add_f32_e32 v100, v101, v103
	v_add_f32_e32 v102, v104, v100
	s_waitcnt vmcnt(30)
	v_mov_b64_e32 v[118:119], v[198:199]
	v_mov_b64_e32 v[120:121], v[200:201]
	v_add_u32_e32 v163, 0xa0000, v162
	global_load_dwordx4 v[198:201], v163, s[16:17] nt
	v_pk_add_f32 v[100:101], v[98:99], v[120:121]
	v_pk_add_f32 v[98:99], v[96:97], v[118:119]
	v_mul_f32_e32 v97, v101, v101
	v_mul_f32_e32 v96, v99, v99
	v_fmac_f32_e32 v96, v98, v98
	v_fmac_f32_e32 v97, v100, v100
	v_add_f32_e32 v96, v96, v97
	v_add_f32_e32 v96, v102, v96
	ds_bpermute_b32 v97, v116, v96
	global_store_dwordx4 v[124:125], v[98:101], off offset:576
	s_waitcnt lgkmcnt(0)
	v_add_f32_e32 v96, v96, v97
	ds_bpermute_b32 v97, v114, v96
	v_cvt_pk_bf16_f32 v98, v98, v99
	v_cvt_pk_bf16_f32 v99, v100, v101
	global_store_dwordx2 v[122:123], v[98:99], off offset:288
	s_and_saveexec_b64 s[58:59], s[12:13]
	s_cbranch_execz .LBB0_1041
	s_waitcnt lgkmcnt(0)
	v_add_f32_e32 v98, v96, v97
	v_lshlrev_b64 v[96:97], 6, v[112:113]
	v_lshl_add_u64 v[96:97], s[28:29], 0, v[96:97]
	v_lshl_add_u64 v[96:97], s[56:57], 2, v[96:97]
	s_lshl_b32 s30, s84, 2
	v_lshl_add_u64 v[96:97], v[96:97], 0, s[30:31]
	global_store_dword v[96:97], v98, off
; __device__ __forceinline__ unsigned pk2(float lo, float hi) { unsigned r; asm volatile("v_cvt_pk_bf16_f32 %0, %1, %2" : "=v"(r) : "v"(lo), "v"(hi)); return r; }
;     __device__ __forceinline__ void operator()(const f32x4 (&acc)[2][2][4][2], const Unit& u, int wr, int wc, int fr, int fq) const {
;     ...
;         for (int ai = 0; ai < 2; ++ai)
; #pragma unroll
;             for (int m = 0; m < 4; ++m) {
;                 const int row = row0 + ai * 128 + m * 16; const size_t ro = (size_t)row * DM + col0;
;                 float s = 0.f;
; #pragma unroll
;                 for (int bj = 0; bj < 2; ++bj)
; #pragma unroll
;                     for (int n = 0; n < 2; ++n) {
;                         const size_t o = ro + bj * 128 + n * 16;
;                         const f32x4 xn = *(const f32x4*)(xo + o) + acc[ai][bj][m][n];
;                         *(f32x4*)(xf + o) = xn;
;                         u32x2 w; w.x = pk2(xn[0], xn[1]); w.y = pk2(xn[2], xn[3]); *(u32x2*)(xb + o) = w;
;                         s += (xn[0] * xn[0] + xn[1] * xn[1]) + (xn[2] * xn[2] + xn[3] * xn[3]);
;                     }
;                 s += __shfl_xor(s, 16); s += __shfl_xor(s, 32);
;                 if (fq == 0) ssq[(size_t)row * 16 + u.pn * 4 + wc] = s;
;             }
.LBB0_1041:
	s_or_b64 exec, exec, s[58:59]
	v_or_b32_e32 v96, 32, v138
	s_waitcnt lgkmcnt(0)
	v_ashrrev_i32_e32 v97, 31, v96
	v_lshlrev_b64 v[98:99], 10, v[96:97]
	v_lshl_add_u64 v[102:103], v[98:99], 0, v[136:137]
	v_lshlrev_b64 v[104:105], 2, v[102:103]
	v_lshl_add_u64 v[106:107], s[16:17], 0, v[104:105]
	v_lshl_add_u64 v[102:103], v[102:103], 1, s[26:27]
	v_lshl_add_u64 v[104:105], s[20:21], 0, v[104:105]
	s_waitcnt vmcnt(32)
	v_mov_b64_e32 v[98:99], v[202:203]
	v_mov_b64_e32 v[100:101], v[204:205]
	v_add_u32_e32 v163, 0xa0040, v162
	global_load_dwordx4 v[202:205], v163, s[16:17] nt
	v_pk_add_f32 v[94:95], v[94:95], v[100:101]
	v_pk_add_f32 v[92:93], v[92:93], v[98:99]
	global_store_dwordx4 v[104:105], v[92:95], off
	v_cvt_pk_bf16_f32 v98, v92, v93
	v_cvt_pk_bf16_f32 v99, v94, v95
	global_store_dwordx2 v[102:103], v[98:99], off
	v_mul_f32_e32 v93, v93, v93
	v_mul_f32_e32 v95, v95, v95
	v_fmac_f32_e32 v93, v92, v92
	v_fmac_f32_e32 v95, v94, v94
	v_add_f32_e32 v92, v93, v95
	s_waitcnt vmcnt(34)
	v_mov_b64_e32 v[98:99], v[206:207]
	v_mov_b64_e32 v[100:101], v[208:209]
	v_add_u32_e32 v163, 0xa0200, v162
	global_load_dwordx4 v[206:209], v163, s[16:17] nt
	v_pk_add_f32 v[90:91], v[90:91], v[100:101]
	v_pk_add_f32 v[88:89], v[88:89], v[98:99]
	global_store_dwordx4 v[104:105], v[88:91], off offset:64
	v_cvt_pk_bf16_f32 v98, v88, v89
	v_cvt_pk_bf16_f32 v99, v90, v91
	global_store_dwordx2 v[102:103], v[98:99], off offset:32
	v_mul_f32_e32 v89, v89, v89
	v_mul_f32_e32 v91, v91, v91
	v_fmac_f32_e32 v89, v88, v88
	v_fmac_f32_e32 v91, v90, v90
	v_add_f32_e32 v88, v89, v91
	v_add_f32_e32 v88, v92, v88
	s_waitcnt vmcnt(36)
	v_mov_b64_e32 v[98:99], v[210:211]
	v_mov_b64_e32 v[100:101], v[212:213]
	v_add_u32_e32 v163, 0xa0240, v162
	global_load_dwordx4 v[210:213], v163, s[16:17] nt
	v_pk_add_f32 v[86:87], v[86:87], v[100:101]
	v_pk_add_f32 v[84:85], v[84:85], v[98:99]
	global_store_dwordx4 v[104:105], v[84:87], off offset:512
	v_cvt_pk_bf16_f32 v98, v84, v85
	v_cvt_pk_bf16_f32 v99, v86, v87
	global_store_dwordx2 v[102:103], v[98:99], off offset:256
	v_mul_f32_e32 v85, v85, v85
	v_mul_f32_e32 v87, v87, v87
	v_fmac_f32_e32 v85, v84, v84
	v_fmac_f32_e32 v87, v86, v86
	v_add_f32_e32 v84, v85, v87
	v_add_f32_e32 v86, v88, v84
	s_waitcnt vmcnt(38)
	v_mov_b64_e32 v[98:99], v[232:233]
	v_mov_b64_e32 v[100:101], v[234:235]
	v_add_u32_e32 v163, 0xb0000, v162
	global_load_dwordx4 v[232:235], v163, s[16:17] nt
	v_pk_add_f32 v[84:85], v[82:83], v[100:101]
	v_pk_add_f32 v[82:83], v[80:81], v[98:99]
	v_mul_f32_e32 v81, v85, v85
	v_mul_f32_e32 v80, v83, v83
	v_fmac_f32_e32 v80, v82, v82
	v_fmac_f32_e32 v81, v84, v84
	v_add_f32_e32 v80, v80, v81
	v_add_f32_e32 v80, v86, v80
	ds_bpermute_b32 v81, v116, v80
	global_store_dwordx4 v[104:105], v[82:85], off offset:576
	s_waitcnt lgkmcnt(0)
	v_add_f32_e32 v80, v80, v81
	ds_bpermute_b32 v81, v114, v80
	v_cvt_pk_bf16_f32 v82, v82, v83
	v_cvt_pk_bf16_f32 v83, v84, v85
	global_store_dwordx2 v[102:103], v[82:83], off offset:288
	s_and_saveexec_b64 s[58:59], s[12:13]
	s_cbranch_execz .LBB0_1043
	s_waitcnt lgkmcnt(0)
	v_add_f32_e32 v82, v80, v81
	v_lshlrev_b64 v[80:81], 6, v[96:97]
	v_lshl_add_u64 v[80:81], s[28:29], 0, v[80:81]
	v_lshl_add_u64 v[80:81], s[56:57], 2, v[80:81]
	s_lshl_b32 s30, s84, 2
	v_lshl_add_u64 v[80:81], v[80:81], 0, s[30:31]
	global_store_dword v[80:81], v82, off
.LBB0_1043:
	s_or_b64 exec, exec, s[58:59]
	v_or_b32_e32 v80, 48, v138
	s_waitcnt lgkmcnt(0)
	v_ashrrev_i32_e32 v81, 31, v80
	v_lshlrev_b64 v[82:83], 10, v[80:81]
	v_lshl_add_u64 v[86:87], v[82:83], 0, v[136:137]
	v_lshlrev_b64 v[88:89], 2, v[86:87]
	v_lshl_add_u64 v[90:91], s[16:17], 0, v[88:89]
	v_lshl_add_u64 v[86:87], v[86:87], 1, s[26:27]
	v_lshl_add_u64 v[88:89], s[20:21], 0, v[88:89]
	s_waitcnt vmcnt(40)
	v_mov_b64_e32 v[82:83], v[236:237]
	v_mov_b64_e32 v[84:85], v[238:239]
	v_add_u32_e32 v163, 0xb0040, v162
	global_load_dwordx4 v[236:239], v163, s[16:17] nt
	v_pk_add_f32 v[78:79], v[78:79], v[84:85]
	v_pk_add_f32 v[76:77], v[76:77], v[82:83]
	global_store_dwordx4 v[88:89], v[76:79], off
	v_cvt_pk_bf16_f32 v82, v76, v77
	v_cvt_pk_bf16_f32 v83, v78, v79
	global_store_dwordx2 v[86:87], v[82:83], off
	v_mul_f32_e32 v77, v77, v77
	v_mul_f32_e32 v79, v79, v79
	v_fmac_f32_e32 v77, v76, v76
	v_fmac_f32_e32 v79, v78, v78
	v_add_f32_e32 v76, v77, v79
	s_waitcnt vmcnt(42)
	v_mov_b64_e32 v[82:83], v[240:241]
	v_mov_b64_e32 v[84:85], v[242:243]
	v_add_u32_e32 v163, 0xb0200, v162
	global_load_dwordx4 v[240:243], v163, s[16:17] nt
	v_pk_add_f32 v[74:75], v[74:75], v[84:85]
	v_pk_add_f32 v[72:73], v[72:73], v[82:83]
	global_store_dwordx4 v[88:89], v[72:75], off offset:64
	v_cvt_pk_bf16_f32 v82, v72, v73
	v_cvt_pk_bf16_f32 v83, v74, v75
	global_store_dwordx2 v[86:87], v[82:83], off offset:32
	v_mul_f32_e32 v73, v73, v73
	v_mul_f32_e32 v75, v75, v75
	v_fmac_f32_e32 v73, v72, v72
	v_fmac_f32_e32 v75, v74, v74
	v_add_f32_e32 v72, v73, v75
	v_add_f32_e32 v72, v76, v72
	s_waitcnt vmcnt(44)
	v_mov_b64_e32 v[82:83], v[244:245]
	v_mov_b64_e32 v[84:85], v[246:247]
	v_add_u32_e32 v163, 0xb0240, v162
	global_load_dwordx4 v[244:247], v163, s[16:17] nt
	v_pk_add_f32 v[70:71], v[70:71], v[84:85]
	v_pk_add_f32 v[68:69], v[68:69], v[82:83]
	global_store_dwordx4 v[88:89], v[68:71], off offset:512
	v_cvt_pk_bf16_f32 v82, v68, v69
	v_cvt_pk_bf16_f32 v83, v70, v71
	global_store_dwordx2 v[86:87], v[82:83], off offset:256
	v_mul_f32_e32 v69, v69, v69
	v_mul_f32_e32 v71, v71, v71
	v_fmac_f32_e32 v69, v68, v68
	v_fmac_f32_e32 v71, v70, v70
	v_add_f32_e32 v68, v69, v71
	v_add_f32_e32 v70, v72, v68
	s_waitcnt vmcnt(46)
	v_mov_b64_e32 v[82:83], v[248:249]
	v_mov_b64_e32 v[84:85], v[250:251]
	v_pk_add_f32 v[68:69], v[66:67], v[84:85]
	v_pk_add_f32 v[66:67], v[64:65], v[82:83]
	v_mul_f32_e32 v65, v69, v69
	v_mul_f32_e32 v64, v67, v67
	v_fmac_f32_e32 v64, v66, v66
	v_fmac_f32_e32 v65, v68, v68
	v_add_f32_e32 v64, v64, v65
	v_add_f32_e32 v64, v70, v64
	ds_bpermute_b32 v65, v116, v64
	global_store_dwordx4 v[88:89], v[66:69], off offset:576
	s_waitcnt lgkmcnt(0)
	v_add_f32_e32 v64, v64, v65
	ds_bpermute_b32 v65, v114, v64
	v_cvt_pk_bf16_f32 v66, v66, v67
	v_cvt_pk_bf16_f32 v67, v68, v69
	global_store_dwordx2 v[86:87], v[66:67], off offset:288
	s_and_saveexec_b64 s[58:59], s[12:13]
	s_cbranch_execz .LBB0_1045
	s_waitcnt lgkmcnt(0)
	v_add_f32_e32 v66, v64, v65
	v_lshlrev_b64 v[64:65], 6, v[80:81]
	v_lshl_add_u64 v[64:65], s[28:29], 0, v[64:65]
	v_lshl_add_u64 v[64:65], s[56:57], 2, v[64:65]
	s_lshl_b32 s30, s84, 2
	v_lshl_add_u64 v[64:65], v[64:65], 0, s[30:31]
	global_store_dword v[64:65], v66, off

; __device__ __forceinline__ unsigned pk2(float lo, float hi) { unsigned r; asm volatile("v_cvt_pk_bf16_f32 %0, %1, %2" : "=v"(r) : "v"(lo), "v"(hi)); return r; }
;     __device__ __forceinline__ void operator()(const f32x4 (&acc)[2][2][4][2], const Unit& u, int wr, int wc, int fr, int fq) const {
;         const int row0 = u.pm * 256 + wr * 64 + fr, col0 = u.pn * 256 + wc * 32 + 4 * fq;
;         const float* xo = (u.pm < 64) ? xoldA : (xoldB - (size_t)T_P * DM);
; #pragma unroll
;         for (int ai = 0; ai < 2; ++ai)
; #pragma unroll
;             for (int m = 0; m < 4; ++m) {
;                 const int row = row0 + ai * 128 + m * 16; const size_t ro = (size_t)row * DM + col0;
;                 float s = 0.f;
; #pragma unroll
;                 for (int bj = 0; bj < 2; ++bj)
; #pragma unroll
;                     for (int n = 0; n < 2; ++n) {
;                         const size_t o = ro + bj * 128 + n * 16;
;                         const f32x4 xn = *(const f32x4*)(xo + o) + acc[ai][bj][m][n];
;                         *(f32x4*)(xf + o) = xn;
;                         u32x2 w; w.x = pk2(xn[0], xn[1]); w.y = pk2(xn[2], xn[3]); *(u32x2*)(xb + o) = w;
;                         s += (xn[0] * xn[0] + xn[1] * xn[1]) + (xn[2] * xn[2] + xn[3] * xn[3]);
;                     }
;                 s += __shfl_xor(s, 16); s += __shfl_xor(s, 32);
;                 if (fq == 0) ssq[(size_t)row * 16 + u.pn * 4 + wc] = s;
;             }
;     }
.LBB0_1922:
	v_lshl_add_u32 v146, s77, 8, v148
	v_lshl_or_b32 v142, s40, 8, v150
	v_ashrrev_i32_e32 v147, 31, v146
	v_ashrrev_i32_e32 v143, 31, v142
	v_lshlrev_b64 v[154:155], 10, v[146:147]
	s_cmp_lt_i32 s77, 64
	v_lshl_add_u64 v[158:159], v[154:155], 0, v[142:143]
	s_cselect_b32 s15, s25, -1
	s_cselect_b32 s14, s24, 0xfc000000
	v_lshlrev_b64 v[160:161], 2, v[158:159]
	v_lshl_add_u64 v[162:163], s[14:15], 0, v[160:161]
	v_subrev_u32_e32 v172, s14, v162
	v_add_u32_e32 v173, 0x0, v172
	global_load_dwordx4 v[174:177], v173, s[14:15] nt
	v_add_u32_e32 v173, 0x40, v172
	global_load_dwordx4 v[178:181], v173, s[14:15] nt
	v_add_u32_e32 v173, 0x200, v172
	global_load_dwordx4 v[182:185], v173, s[14:15] nt
	v_add_u32_e32 v173, 0x240, v172
	global_load_dwordx4 v[186:189], v173, s[14:15] nt
	v_add_u32_e32 v173, 0x10000, v172
	global_load_dwordx4 v[190:193], v173, s[14:15] nt
	v_add_u32_e32 v173, 0x10040, v172
	global_load_dwordx4 v[194:197], v173, s[14:15] nt
	v_add_u32_e32 v173, 0x10200, v172
	global_load_dwordx4 v[198:201], v173, s[14:15] nt
	v_add_u32_e32 v173, 0x10240, v172
	global_load_dwordx4 v[202:205], v173, s[14:15] nt
	v_add_u32_e32 v173, 0x20000, v172
	global_load_dwordx4 v[206:209], v173, s[14:15] nt
	v_add_u32_e32 v173, 0x20040, v172
	global_load_dwordx4 v[210:213], v173, s[14:15] nt
	v_add_u32_e32 v173, 0x20200, v172
	global_load_dwordx4 v[214:217], v173, s[14:15] nt
	v_add_u32_e32 v173, 0x20240, v172
	global_load_dwordx4 v[218:221], v173, s[14:15] nt
	v_add_u32_e32 v173, 0x30000, v172
	global_load_dwordx4 v[232:235], v173, s[14:15] nt
	v_add_u32_e32 v173, 0x30040, v172
	global_load_dwordx4 v[236:239], v173, s[14:15] nt
	v_add_u32_e32 v173, 0x30200, v172
	global_load_dwordx4 v[240:243], v173, s[14:15] nt
	v_add_u32_e32 v173, 0x30240, v172
	global_load_dwordx4 v[244:247], v173, s[14:15] nt
	v_add_u32_e32 v173, 0x80000, v172
	global_load_dwordx4 v[248:251], v173, s[14:15] nt
	v_add_u32_e32 v173, 0x80040, v172
	global_load_dwordx4 v[252:255], v173, s[14:15] nt
	v_lshl_add_u64 v[164:165], v[158:159], 1, s[20:21]
	v_lshl_add_u64 v[170:171], s[24:25], 0, v[160:161]
	v_xor_b32_e32 v153, 32, v152
	s_lshl_b32 s40, s40, 2
	s_ashr_i32 s41, s40, 31
	s_waitcnt vmcnt(17)
	v_mov_b64_e32 v[154:155], v[174:175]
	v_mov_b64_e32 v[156:157], v[176:177]
	v_add_u32_e32 v173, 0x80200, v172
	global_load_dwordx4 v[174:177], v173, s[14:15] nt
	v_pk_add_f32 v[126:127], v[126:127], v[156:157]
	v_pk_add_f32 v[124:125], v[124:125], v[154:155]
	global_store_dwordx4 v[170:171], v[124:127], off
	v_cvt_pk_bf16_f32 v154, v124, v125
	v_cvt_pk_bf16_f32 v155, v126, v127
	global_store_dwordx2 v[164:165], v[154:155], off
	s_waitcnt vmcnt(19)
	v_mov_b64_e32 v[154:155], v[178:179]
	v_mov_b64_e32 v[156:157], v[180:181]
	v_add_u32_e32 v173, 0x80240, v172
	global_load_dwordx4 v[178:181], v173, s[14:15] nt
	v_pk_add_f32 v[122:123], v[122:123], v[156:157]
	v_pk_add_f32 v[120:121], v[120:121], v[154:155]
	global_store_dwordx4 v[170:171], v[120:123], off offset:64
	v_cvt_pk_bf16_f32 v154, v120, v121
	v_cvt_pk_bf16_f32 v155, v122, v123
	global_store_dwordx2 v[164:165], v[154:155], off offset:32
	s_waitcnt vmcnt(21)
	v_mov_b64_e32 v[154:155], v[182:183]
	v_mov_b64_e32 v[156:157], v[184:185]
	v_add_u32_e32 v173, 0x90000, v172
	global_load_dwordx4 v[182:185], v173, s[14:15] nt
	v_pk_add_f32 v[156:157], v[118:119], v[156:157]
	v_pk_add_f32 v[154:155], v[116:117], v[154:155]
	global_store_dwordx4 v[170:171], v[154:157], off offset:512
	v_cvt_pk_bf16_f32 v116, v154, v155
	v_cvt_pk_bf16_f32 v117, v156, v157
	global_store_dwordx2 v[164:165], v[116:117], off offset:256
	v_mul_f32_e32 v118, v125, v125
	v_mul_f32_e32 v119, v127, v127
	v_fmac_f32_e32 v118, v124, v124
	v_fmac_f32_e32 v119, v126, v126
	v_add_f32_e32 v118, v118, v119
	v_mul_f32_e32 v119, v121, v121
	v_mul_f32_e32 v121, v123, v123
	v_fmac_f32_e32 v119, v120, v120
	v_fmac_f32_e32 v121, v122, v122
	v_add_f32_e32 v119, v119, v121
	v_add_f32_e32 v118, v118, v119
	v_mul_f32_e32 v119, v155, v155
	v_mul_f32_e32 v120, v157, v157
	v_fmac_f32_e32 v119, v154, v154
	v_fmac_f32_e32 v120, v156, v156
	v_add_f32_e32 v119, v119, v120
	v_and_b32_e32 v117, 64, v152
	v_add_f32_e32 v122, v118, v119
	v_xor_b32_e32 v116, 16, v152
	v_add_u32_e32 v117, 64, v117
	v_cmp_lt_i32_e32 vcc, v116, v117
	s_waitcnt vmcnt(23)
	v_mov_b64_e32 v[158:159], v[186:187]
	v_mov_b64_e32 v[160:161], v[188:189]
	v_add_u32_e32 v173, 0x90040, v172
	global_load_dwordx4 v[186:189], v173, s[14:15] nt
	v_pk_add_f32 v[120:121], v[114:115], v[160:161]
	v_pk_add_f32 v[118:119], v[112:113], v[158:159]
	v_mul_f32_e32 v113, v121, v121
	v_mul_f32_e32 v112, v119, v119
	v_fmac_f32_e32 v112, v118, v118
	v_fmac_f32_e32 v113, v120, v120
	v_cndmask_b32_e32 v116, v152, v116, vcc
	v_add_f32_e32 v112, v112, v113
	v_lshlrev_b32_e32 v116, 2, v116
	v_add_f32_e32 v112, v122, v112
	ds_bpermute_b32 v113, v116, v112
	v_cmp_lt_i32_e32 vcc, v153, v117
	global_store_dwordx4 v[170:171], v[118:121], off offset:576
	s_waitcnt lgkmcnt(0)
	v_add_f32_e32 v112, v112, v113
	v_cndmask_b32_e32 v114, v152, v153, vcc
	v_lshlrev_b32_e32 v114, 2, v114
	ds_bpermute_b32 v113, v114, v112
	v_cvt_pk_bf16_f32 v118, v118, v119
	v_cvt_pk_bf16_f32 v119, v120, v121
	global_store_dwordx2 v[164:165], v[118:119], off offset:288
	s_and_saveexec_b64 s[42:43], s[10:11]
	s_cbranch_execz .LBB0_1924
	s_waitcnt lgkmcnt(0)
	v_add_f32_e32 v115, v112, v113
	v_lshlrev_b64 v[112:113], 6, v[146:147]
	v_lshl_add_u64 v[112:113], s[22:23], 0, v[112:113]
	v_lshl_add_u64 v[112:113], s[40:41], 2, v[112:113]
	s_lshl_b32 s30, s67, 2
	v_lshl_add_u64 v[112:113], v[112:113], 0, s[30:31]
	global_store_dword v[112:113], v115, off
; __device__ __forceinline__ unsigned pk2(float lo, float hi) { unsigned r; asm volatile("v_cvt_pk_bf16_f32 %0, %1, %2" : "=v"(r) : "v"(lo), "v"(hi)); return r; }
;     __device__ __forceinline__ void operator()(const f32x4 (&acc)[2][2][4][2], const Unit& u, int wr, int wc, int fr, int fq) const {
;     ...
;         for (int ai = 0; ai < 2; ++ai)
; #pragma unroll
;             for (int m = 0; m < 4; ++m) {
;                 const int row = row0 + ai * 128 + m * 16; const size_t ro = (size_t)row * DM + col0;
;                 float s = 0.f;
; #pragma unroll
;                 for (int bj = 0; bj < 2; ++bj)
; #pragma unroll
;                     for (int n = 0; n < 2; ++n) {
;                         const size_t o = ro + bj * 128 + n * 16;
;                         const f32x4 xn = *(const f32x4*)(xo + o) + acc[ai][bj][m][n];
;                         *(f32x4*)(xf + o) = xn;
;                         u32x2 w; w.x = pk2(xn[0], xn[1]); w.y = pk2(xn[2], xn[3]); *(u32x2*)(xb + o) = w;
;                         s += (xn[0] * xn[0] + xn[1] * xn[1]) + (xn[2] * xn[2] + xn[3] * xn[3]);
;                     }
;                 s += __shfl_xor(s, 16); s += __shfl_xor(s, 32);
;                 if (fq == 0) ssq[(size_t)row * 16 + u.pn * 4 + wc] = s;
;             }
.LBB0_1924:
	s_or_b64 exec, exec, s[42:43]
	v_or_b32_e32 v112, 16, v146
	s_waitcnt lgkmcnt(0)
	v_ashrrev_i32_e32 v113, 31, v112
	v_lshlrev_b64 v[118:119], 10, v[112:113]
	v_lshl_add_u64 v[122:123], v[118:119], 0, v[142:143]
	v_lshlrev_b64 v[124:125], 2, v[122:123]
	v_lshl_add_u64 v[126:127], s[14:15], 0, v[124:125]
	v_lshl_add_u64 v[122:123], v[122:123], 1, s[20:21]
	v_lshl_add_u64 v[124:125], s[24:25], 0, v[124:125]
	s_waitcnt vmcnt(25)
	v_mov_b64_e32 v[118:119], v[190:191]
	v_mov_b64_e32 v[120:121], v[192:193]
	v_add_u32_e32 v173, 0x90200, v172
	global_load_dwordx4 v[190:193], v173, s[14:15] nt
	v_pk_add_f32 v[110:111], v[110:111], v[120:121]
	v_pk_add_f32 v[108:109], v[108:109], v[118:119]
	global_store_dwordx4 v[124:125], v[108:111], off
	v_cvt_pk_bf16_f32 v118, v108, v109
	v_cvt_pk_bf16_f32 v119, v110, v111
	global_store_dwordx2 v[122:123], v[118:119], off
	v_mul_f32_e32 v109, v109, v109
	v_mul_f32_e32 v111, v111, v111
	v_fmac_f32_e32 v109, v108, v108
	v_fmac_f32_e32 v111, v110, v110
	v_add_f32_e32 v108, v109, v111
	s_waitcnt vmcnt(27)
	v_mov_b64_e32 v[118:119], v[194:195]
	v_mov_b64_e32 v[120:121], v[196:197]
	v_add_u32_e32 v173, 0x90240, v172
	global_load_dwordx4 v[194:197], v173, s[14:15] nt
	v_pk_add_f32 v[106:107], v[106:107], v[120:121]
	v_pk_add_f32 v[104:105], v[104:105], v[118:119]
	global_store_dwordx4 v[124:125], v[104:107], off offset:64
	v_cvt_pk_bf16_f32 v118, v104, v105
	v_cvt_pk_bf16_f32 v119, v106, v107
	global_store_dwordx2 v[122:123], v[118:119], off offset:32
	v_mul_f32_e32 v105, v105, v105
	v_mul_f32_e32 v107, v107, v107
	v_fmac_f32_e32 v105, v104, v104
	v_fmac_f32_e32 v107, v106, v106
	v_add_f32_e32 v104, v105, v107
	v_add_f32_e32 v104, v108, v104
	s_waitcnt vmcnt(29)
	v_mov_b64_e32 v[118:119], v[198:199]
	v_mov_b64_e32 v[120:121], v[200:201]
	v_add_u32_e32 v173, 0xa0000, v172
	global_load_dwordx4 v[198:201], v173, s[14:15] nt
	v_pk_add_f32 v[102:103], v[102:103], v[120:121]
	v_pk_add_f32 v[100:101], v[100:101], v[118:119]
	global_store_dwordx4 v[124:125], v[100:103], off offset:512
	v_cvt_pk_bf16_f32 v118, v100, v101
	v_cvt_pk_bf16_f32 v119, v102, v103
	global_store_dwordx2 v[122:123], v[118:119], off offset:256
	v_mul_f32_e32 v101, v101, v101
	v_mul_f32_e32 v103, v103, v103
	v_fmac_f32_e32 v101, v100, v100
	v_fmac_f32_e32 v103, v102, v102
	v_add_f32_e32 v100, v101, v103
	v_add_f32_e32 v102, v104, v100
	s_waitcnt vmcnt(31)
	v_mov_b64_e32 v[118:119], v[202:203]
	v_mov_b64_e32 v[120:121], v[204:205]
	v_add_u32_e32 v173, 0xa0040, v172
	global_load_dwordx4 v[202:205], v173, s[14:15] nt
	v_pk_add_f32 v[100:101], v[98:99], v[120:121]
	v_pk_add_f32 v[98:99], v[96:97], v[118:119]
	v_mul_f32_e32 v97, v101, v101
	v_mul_f32_e32 v96, v99, v99
	v_fmac_f32_e32 v96, v98, v98
	v_fmac_f32_e32 v97, v100, v100
	v_add_f32_e32 v96, v96, v97
	v_add_f32_e32 v96, v102, v96
	ds_bpermute_b32 v97, v116, v96
	global_store_dwordx4 v[124:125], v[98:101], off offset:576
	s_waitcnt lgkmcnt(0)
	v_add_f32_e32 v96, v96, v97
	ds_bpermute_b32 v97, v114, v96
	v_cvt_pk_bf16_f32 v98, v98, v99
	v_cvt_pk_bf16_f32 v99, v100, v101
	global_store_dwordx2 v[122:123], v[98:99], off offset:288
	s_and_saveexec_b64 s[42:43], s[10:11]
	s_cbranch_execz .LBB0_1926
	s_waitcnt lgkmcnt(0)
	v_add_f32_e32 v98, v96, v97
	v_lshlrev_b64 v[96:97], 6, v[112:113]
	v_lshl_add_u64 v[96:97], s[22:23], 0, v[96:97]
	v_lshl_add_u64 v[96:97], s[40:41], 2, v[96:97]
	s_lshl_b32 s30, s67, 2
	v_lshl_add_u64 v[96:97], v[96:97], 0, s[30:31]
	global_store_dword v[96:97], v98, off
; __device__ __forceinline__ unsigned pk2(float lo, float hi) { unsigned r; asm volatile("v_cvt_pk_bf16_f32 %0, %1, %2" : "=v"(r) : "v"(lo), "v"(hi)); return r; }
;     __device__ __forceinline__ void operator()(const f32x4 (&acc)[2][2][4][2], const Unit& u, int wr, int wc, int fr, int fq) const {
;     ...
;         for (int ai = 0; ai < 2; ++ai)
; #pragma unroll
;             for (int m = 0; m < 4; ++m) {
;                 const int row = row0 + ai * 128 + m * 16; const size_t ro = (size_t)row * DM + col0;
;                 float s = 0.f;
; #pragma unroll
;                 for (int bj = 0; bj < 2; ++bj)
; #pragma unroll
;                     for (int n = 0; n < 2; ++n) {
;                         const size_t o = ro + bj * 128 + n * 16;
;                         const f32x4 xn = *(const f32x4*)(xo + o) + acc[ai][bj][m][n];
;                         *(f32x4*)(xf + o) = xn;
;                         u32x2 w; w.x = pk2(xn[0], xn[1]); w.y = pk2(xn[2], xn[3]); *(u32x2*)(xb + o) = w;
;                         s += (xn[0] * xn[0] + xn[1] * xn[1]) + (xn[2] * xn[2] + xn[3] * xn[3]);
;                     }
;                 s += __shfl_xor(s, 16); s += __shfl_xor(s, 32);
;                 if (fq == 0) ssq[(size_t)row * 16 + u.pn * 4 + wc] = s;
;             }
.LBB0_1926:
	s_or_b64 exec, exec, s[42:43]
	v_or_b32_e32 v96, 32, v146
	s_waitcnt lgkmcnt(0)
	v_ashrrev_i32_e32 v97, 31, v96
	v_lshlrev_b64 v[98:99], 10, v[96:97]
	v_lshl_add_u64 v[102:103], v[98:99], 0, v[142:143]
	v_lshlrev_b64 v[104:105], 2, v[102:103]
	v_lshl_add_u64 v[106:107], s[14:15], 0, v[104:105]
	v_lshl_add_u64 v[102:103], v[102:103], 1, s[20:21]
	v_lshl_add_u64 v[104:105], s[24:25], 0, v[104:105]
	s_waitcnt vmcnt(33)
	v_mov_b64_e32 v[98:99], v[206:207]
	v_mov_b64_e32 v[100:101], v[208:209]
	v_add_u32_e32 v173, 0xa0200, v172
	global_load_dwordx4 v[206:209], v173, s[14:15] nt
	v_pk_add_f32 v[94:95], v[94:95], v[100:101]
	v_pk_add_f32 v[92:93], v[92:93], v[98:99]
	global_store_dwordx4 v[104:105], v[92:95], off
	v_cvt_pk_bf16_f32 v98, v92, v93
	v_cvt_pk_bf16_f32 v99, v94, v95
	global_store_dwordx2 v[102:103], v[98:99], off
	v_mul_f32_e32 v93, v93, v93
	v_mul_f32_e32 v95, v95, v95
	v_fmac_f32_e32 v93, v92, v92
	v_fmac_f32_e32 v95, v94, v94
	v_add_f32_e32 v92, v93, v95
	s_waitcnt vmcnt(35)
	v_mov_b64_e32 v[98:99], v[210:211]
	v_mov_b64_e32 v[100:101], v[212:213]
	v_add_u32_e32 v173, 0xa0240, v172
	global_load_dwordx4 v[210:213], v173, s[14:15] nt
	v_pk_add_f32 v[90:91], v[90:91], v[100:101]
	v_pk_add_f32 v[88:89], v[88:89], v[98:99]
	global_store_dwordx4 v[104:105], v[88:91], off offset:64
	v_cvt_pk_bf16_f32 v98, v88, v89
	v_cvt_pk_bf16_f32 v99, v90, v91
	global_store_dwordx2 v[102:103], v[98:99], off offset:32
	v_mul_f32_e32 v89, v89, v89
	v_mul_f32_e32 v91, v91, v91
	v_fmac_f32_e32 v89, v88, v88
	v_fmac_f32_e32 v91, v90, v90
	v_add_f32_e32 v88, v89, v91
	v_add_f32_e32 v88, v92, v88
	s_waitcnt vmcnt(37)
	v_mov_b64_e32 v[98:99], v[214:215]
	v_mov_b64_e32 v[100:101], v[216:217]
	v_add_u32_e32 v173, 0xb0000, v172
	global_load_dwordx4 v[214:217], v173, s[14:15] nt
	v_pk_add_f32 v[86:87], v[86:87], v[100:101]
	v_pk_add_f32 v[84:85], v[84:85], v[98:99]
	global_store_dwordx4 v[104:105], v[84:87], off offset:512
	v_cvt_pk_bf16_f32 v98, v84, v85
	v_cvt_pk_bf16_f32 v99, v86, v87
	global_store_dwordx2 v[102:103], v[98:99], off offset:256
	v_mul_f32_e32 v85, v85, v85
	v_mul_f32_e32 v87, v87, v87
	v_fmac_f32_e32 v85, v84, v84
	v_fmac_f32_e32 v87, v86, v86
	v_add_f32_e32 v84, v85, v87
	v_add_f32_e32 v86, v88, v84
	s_waitcnt vmcnt(39)
	v_mov_b64_e32 v[98:99], v[218:219]
	v_mov_b64_e32 v[100:101], v[220:221]
	v_add_u32_e32 v173, 0xb0040, v172
	global_load_dwordx4 v[218:221], v173, s[14:15] nt
	v_pk_add_f32 v[84:85], v[82:83], v[100:101]
	v_pk_add_f32 v[82:83], v[80:81], v[98:99]
	v_mul_f32_e32 v81, v85, v85
	v_mul_f32_e32 v80, v83, v83
	v_fmac_f32_e32 v80, v82, v82
	v_fmac_f32_e32 v81, v84, v84
	v_add_f32_e32 v80, v80, v81
	v_add_f32_e32 v80, v86, v80
	ds_bpermute_b32 v81, v116, v80
	global_store_dwordx4 v[104:105], v[82:85], off offset:576
	s_waitcnt lgkmcnt(0)
	v_add_f32_e32 v80, v80, v81
	ds_bpermute_b32 v81, v114, v80
	v_cvt_pk_bf16_f32 v82, v82, v83
	v_cvt_pk_bf16_f32 v83, v84, v85
	global_store_dwordx2 v[102:103], v[82:83], off offset:288
	s_and_saveexec_b64 s[42:43], s[10:11]
	s_cbranch_execz .LBB0_1928
	s_waitcnt lgkmcnt(0)
	v_add_f32_e32 v82, v80, v81
	v_lshlrev_b64 v[80:81], 6, v[96:97]
	v_lshl_add_u64 v[80:81], s[22:23], 0, v[80:81]
	v_lshl_add_u64 v[80:81], s[40:41], 2, v[80:81]
	s_lshl_b32 s30, s67, 2
	v_lshl_add_u64 v[80:81], v[80:81], 0, s[30:31]
	global_store_dword v[80:81], v82, off
.LBB0_1928:
	s_or_b64 exec, exec, s[42:43]
	v_or_b32_e32 v80, 48, v146
	s_waitcnt lgkmcnt(0)
	v_ashrrev_i32_e32 v81, 31, v80
	v_lshlrev_b64 v[82:83], 10, v[80:81]
	v_lshl_add_u64 v[86:87], v[82:83], 0, v[142:143]
	v_lshlrev_b64 v[88:89], 2, v[86:87]
	v_lshl_add_u64 v[90:91], s[14:15], 0, v[88:89]
	v_lshl_add_u64 v[86:87], v[86:87], 1, s[20:21]
	v_lshl_add_u64 v[88:89], s[24:25], 0, v[88:89]
	s_waitcnt vmcnt(41)
	v_mov_b64_e32 v[82:83], v[232:233]
	v_mov_b64_e32 v[84:85], v[234:235]
	v_add_u32_e32 v173, 0xb0200, v172
	global_load_dwordx4 v[232:235], v173, s[14:15] nt
	v_pk_add_f32 v[78:79], v[78:79], v[84:85]
	v_pk_add_f32 v[76:77], v[76:77], v[82:83]
	global_store_dwordx4 v[88:89], v[76:79], off
	v_cvt_pk_bf16_f32 v82, v76, v77
	v_cvt_pk_bf16_f32 v83, v78, v79
	global_store_dwordx2 v[86:87], v[82:83], off
	v_mul_f32_e32 v77, v77, v77
	v_mul_f32_e32 v79, v79, v79
	v_fmac_f32_e32 v77, v76, v76
	v_fmac_f32_e32 v79, v78, v78
	v_add_f32_e32 v76, v77, v79
	s_waitcnt vmcnt(43)
	v_mov_b64_e32 v[82:83], v[236:237]
	v_mov_b64_e32 v[84:85], v[238:239]
	v_add_u32_e32 v173, 0xb0240, v172
	global_load_dwordx4 v[236:239], v173, s[14:15] nt
	v_pk_add_f32 v[74:75], v[74:75], v[84:85]
	v_pk_add_f32 v[72:73], v[72:73], v[82:83]
	global_store_dwordx4 v[88:89], v[72:75], off offset:64
	v_cvt_pk_bf16_f32 v82, v72, v73
	v_cvt_pk_bf16_f32 v83, v74, v75
	global_store_dwordx2 v[86:87], v[82:83], off offset:32
	v_mul_f32_e32 v73, v73, v73
	v_mul_f32_e32 v75, v75, v75
	v_fmac_f32_e32 v73, v72, v72
	v_fmac_f32_e32 v75, v74, v74
	v_add_f32_e32 v72, v73, v75
	v_add_f32_e32 v72, v76, v72
	s_waitcnt vmcnt(45)
	v_mov_b64_e32 v[82:83], v[240:241]
	v_mov_b64_e32 v[84:85], v[242:243]
	v_pk_add_f32 v[70:71], v[70:71], v[84:85]
	v_pk_add_f32 v[68:69], v[68:69], v[82:83]
	global_store_dwordx4 v[88:89], v[68:71], off offset:512
	v_cvt_pk_bf16_f32 v82, v68, v69
	v_cvt_pk_bf16_f32 v83, v70, v71
	global_store_dwordx2 v[86:87], v[82:83], off offset:256
	v_mul_f32_e32 v69, v69, v69
	v_mul_f32_e32 v71, v71, v71
	v_fmac_f32_e32 v69, v68, v68
	v_fmac_f32_e32 v71, v70, v70
	v_add_f32_e32 v68, v69, v71
	v_add_f32_e32 v70, v72, v68
	s_waitcnt vmcnt(46)
	v_mov_b64_e32 v[82:83], v[244:245]
	v_mov_b64_e32 v[84:85], v[246:247]
	v_pk_add_f32 v[68:69], v[66:67], v[84:85]
	v_pk_add_f32 v[66:67], v[64:65], v[82:83]
	v_mul_f32_e32 v65, v69, v69
	v_mul_f32_e32 v64, v67, v67
	v_fmac_f32_e32 v64, v66, v66
	v_fmac_f32_e32 v65, v68, v68
	v_add_f32_e32 v64, v64, v65
	v_add_f32_e32 v64, v70, v64
	ds_bpermute_b32 v65, v116, v64
	global_store_dwordx4 v[88:89], v[66:69], off offset:576
	s_waitcnt lgkmcnt(0)
	v_add_f32_e32 v64, v64, v65
	ds_bpermute_b32 v65, v114, v64
	v_cvt_pk_bf16_f32 v66, v66, v67
	v_cvt_pk_bf16_f32 v67, v68, v69
	global_store_dwordx2 v[86:87], v[66:67], off offset:288
	s_and_saveexec_b64 s[42:43], s[10:11]
	s_cbranch_execz .LBB0_1930
	s_waitcnt lgkmcnt(0)
	v_add_f32_e32 v66, v64, v65
	v_lshlrev_b64 v[64:65], 6, v[80:81]
	v_lshl_add_u64 v[64:65], s[22:23], 0, v[64:65]
	v_lshl_add_u64 v[64:65], s[40:41], 2, v[64:65]
	s_lshl_b32 s30, s67, 2
	v_lshl_add_u64 v[64:65], v[64:65], 0, s[30:31]
	global_store_dword v[64:65], v66, off

; __device__ __forceinline__ unsigned pk2(float lo, float hi) { unsigned r; asm volatile("v_cvt_pk_bf16_f32 %0, %1, %2" : "=v"(r) : "v"(lo), "v"(hi)); return r; }
;     __device__ __forceinline__ void operator()(const f32x4 (&acc)[2][2][4][2], const Unit& u, int wr, int wc, int fr, int fq) const {
;         const int row0 = u.pm * 256 + wr * 64 + fr, col0 = u.pn * 256 + wc * 32 + 4 * fq;
;         const float* xo = (u.pm < 64) ? xoldA : (xoldB - (size_t)T_P * DM);
; #pragma unroll
;         for (int ai = 0; ai < 2; ++ai)
; #pragma unroll
;             for (int m = 0; m < 4; ++m) {
;                 const int row = row0 + ai * 128 + m * 16; const size_t ro = (size_t)row * DM + col0;
;                 float s = 0.f;
; #pragma unroll
;                 for (int bj = 0; bj < 2; ++bj)
; #pragma unroll
;                     for (int n = 0; n < 2; ++n) {
;                         const size_t o = ro + bj * 128 + n * 16;
;                         const f32x4 xn = *(const f32x4*)(xo + o) + acc[ai][bj][m][n];
;                         *(f32x4*)(xf + o) = xn;
;                         u32x2 w; w.x = pk2(xn[0], xn[1]); w.y = pk2(xn[2], xn[3]); *(u32x2*)(xb + o) = w;
;                         s += (xn[0] * xn[0] + xn[1] * xn[1]) + (xn[2] * xn[2] + xn[3] * xn[3]);
;                     }
;                 s += __shfl_xor(s, 16); s += __shfl_xor(s, 32);
;                 if (fq == 0) ssq[(size_t)row * 16 + u.pn * 4 + wc] = s;
;             }
;     }
.LBB0_2178:
	v_lshl_add_u32 v138, s42, 8, v140
	v_lshl_or_b32 v136, s40, 8, v142
	v_ashrrev_i32_e32 v139, 31, v138
	v_ashrrev_i32_e32 v137, 31, v136
	v_lshlrev_b64 v[148:149], 10, v[138:139]
	s_cmp_lt_i32 s42, 64
	v_lshl_add_u64 v[152:153], v[148:149], 0, v[136:137]
	s_cselect_b32 s13, s17, -1
	s_cselect_b32 s12, s16, 0xfc000000
	v_lshlrev_b64 v[154:155], 2, v[152:153]
	v_lshl_add_u64 v[156:157], s[12:13], 0, v[154:155]
	v_subrev_u32_e32 v162, s12, v156
	v_add_u32_e32 v163, 0x0, v162
	global_load_dwordx4 v[170:173], v163, s[12:13] nt
	v_add_u32_e32 v163, 0x40, v162
	global_load_dwordx4 v[174:177], v163, s[12:13] nt
	v_add_u32_e32 v163, 0x200, v162
	global_load_dwordx4 v[178:181], v163, s[12:13] nt
	v_add_u32_e32 v163, 0x240, v162
	global_load_dwordx4 v[182:185], v163, s[12:13] nt
	v_add_u32_e32 v163, 0x10000, v162
	global_load_dwordx4 v[186:189], v163, s[12:13] nt
	v_add_u32_e32 v163, 0x10040, v162
	global_load_dwordx4 v[190:193], v163, s[12:13] nt
	v_add_u32_e32 v163, 0x10200, v162
	global_load_dwordx4 v[194:197], v163, s[12:13] nt
	v_add_u32_e32 v163, 0x10240, v162
	global_load_dwordx4 v[198:201], v163, s[12:13] nt
	v_add_u32_e32 v163, 0x20000, v162
	global_load_dwordx4 v[202:205], v163, s[12:13] nt
	v_add_u32_e32 v163, 0x20040, v162
	global_load_dwordx4 v[206:209], v163, s[12:13] nt
	v_add_u32_e32 v163, 0x20200, v162
	global_load_dwordx4 v[210:213], v163, s[12:13] nt
	v_add_u32_e32 v163, 0x20240, v162
	global_load_dwordx4 v[232:235], v163, s[12:13] nt
	v_add_u32_e32 v163, 0x30000, v162
	global_load_dwordx4 v[236:239], v163, s[12:13] nt
	v_add_u32_e32 v163, 0x30040, v162
	global_load_dwordx4 v[240:243], v163, s[12:13] nt
	v_add_u32_e32 v163, 0x30200, v162
	global_load_dwordx4 v[244:247], v163, s[12:13] nt
	v_add_u32_e32 v163, 0x30240, v162
	global_load_dwordx4 v[248:251], v163, s[12:13] nt
	v_add_u32_e32 v163, 0x80000, v162
	global_load_dwordx4 v[252:255], v163, s[12:13] nt
	v_lshl_add_u64 v[158:159], v[152:153], 1, s[22:23]
	v_lshl_add_u64 v[160:161], s[16:17], 0, v[154:155]
	v_xor_b32_e32 v147, 32, v146
	s_lshl_b32 s40, s40, 2
	s_ashr_i32 s41, s40, 31
	s_waitcnt vmcnt(16)
	v_mov_b64_e32 v[148:149], v[170:171]
	v_mov_b64_e32 v[150:151], v[172:173]
	v_add_u32_e32 v163, 0x80040, v162
	global_load_dwordx4 v[170:173], v163, s[12:13] nt
	v_pk_add_f32 v[126:127], v[126:127], v[150:151]
	v_pk_add_f32 v[124:125], v[124:125], v[148:149]
	global_store_dwordx4 v[160:161], v[124:127], off
	v_cvt_pk_bf16_f32 v148, v124, v125
	v_cvt_pk_bf16_f32 v149, v126, v127
	s_waitcnt vmcnt(17)
	v_mov_b32_e32 v148, v174
	v_mov_b32_e32 v149, v175
	v_mov_b64_e32 v[150:151], v[176:177]
	v_add_u32_e32 v163, 0x80200, v162
	global_load_dwordx4 v[174:177], v163, s[12:13] nt
	v_pk_add_f32 v[122:123], v[122:123], v[150:151]
	v_pk_add_f32 v[120:121], v[120:121], v[148:149]
	global_store_dwordx4 v[160:161], v[120:123], off offset:64
	v_cvt_pk_bf16_f32 v148, v120, v121
	v_cvt_pk_bf16_f32 v149, v122, v123
	s_waitcnt vmcnt(18)
	v_mov_b32_e32 v148, v178
	v_mov_b32_e32 v149, v179
	v_mov_b64_e32 v[150:151], v[180:181]
	v_add_u32_e32 v163, 0x80240, v162
	global_load_dwordx4 v[178:181], v163, s[12:13] nt
	v_pk_add_f32 v[150:151], v[118:119], v[150:151]
	v_pk_add_f32 v[148:149], v[116:117], v[148:149]
	global_store_dwordx4 v[160:161], v[148:151], off offset:512
	v_cvt_pk_bf16_f32 v116, v148, v149
	v_cvt_pk_bf16_f32 v117, v150, v151
	v_mul_f32_e32 v118, v125, v125
	v_mul_f32_e32 v119, v127, v127
	v_fmac_f32_e32 v118, v124, v124
	v_fmac_f32_e32 v119, v126, v126
	v_add_f32_e32 v118, v118, v119
	v_mul_f32_e32 v119, v121, v121
	v_mul_f32_e32 v121, v123, v123
	v_fmac_f32_e32 v119, v120, v120
	v_fmac_f32_e32 v121, v122, v122
	v_add_f32_e32 v119, v119, v121
	v_add_f32_e32 v118, v118, v119
	v_mul_f32_e32 v119, v149, v149
	v_mul_f32_e32 v120, v151, v151
	v_fmac_f32_e32 v119, v148, v148
	v_fmac_f32_e32 v120, v150, v150
	v_add_f32_e32 v119, v119, v120
	v_and_b32_e32 v117, 64, v146
	v_add_f32_e32 v122, v118, v119
	v_xor_b32_e32 v116, 16, v146
	v_add_u32_e32 v117, 64, v117
	v_cmp_lt_i32_e32 vcc, v116, v117
	s_waitcnt vmcnt(19)
	v_mov_b64_e32 v[152:153], v[182:183]
	v_mov_b64_e32 v[154:155], v[184:185]
	v_add_u32_e32 v163, 0x90000, v162
	global_load_dwordx4 v[182:185], v163, s[12:13] nt
	v_pk_add_f32 v[120:121], v[114:115], v[154:155]
	v_pk_add_f32 v[118:119], v[112:113], v[152:153]
	v_mul_f32_e32 v113, v121, v121
	v_mul_f32_e32 v112, v119, v119
	v_fmac_f32_e32 v112, v118, v118
	v_fmac_f32_e32 v113, v120, v120
	v_cndmask_b32_e32 v116, v146, v116, vcc
	v_add_f32_e32 v112, v112, v113
	v_lshlrev_b32_e32 v116, 2, v116
	v_add_f32_e32 v112, v122, v112
	ds_bpermute_b32 v113, v116, v112
	v_cmp_lt_i32_e32 vcc, v147, v117
	global_store_dwordx4 v[160:161], v[118:121], off offset:576
	s_waitcnt lgkmcnt(0)
	v_add_f32_e32 v112, v112, v113
	v_cndmask_b32_e32 v114, v146, v147, vcc
	v_lshlrev_b32_e32 v114, 2, v114
	ds_bpermute_b32 v113, v114, v112
	v_cvt_pk_bf16_f32 v118, v118, v119
	v_cvt_pk_bf16_f32 v119, v120, v121
	s_and_saveexec_b64 s[42:43], s[8:9]
	s_cbranch_execz .LBB0_2180
	s_waitcnt lgkmcnt(0)
	v_add_f32_e32 v115, v112, v113
	v_lshlrev_b64 v[112:113], 6, v[138:139]
	v_lshl_add_u64 v[112:113], s[24:25], 0, v[112:113]
	v_lshl_add_u64 v[112:113], s[40:41], 2, v[112:113]
	s_lshl_b32 s26, s74, 2
	v_lshl_add_u64 v[112:113], v[112:113], 0, s[26:27]
	global_store_dword v[112:113], v115, off
; __device__ __forceinline__ unsigned pk2(float lo, float hi) { unsigned r; asm volatile("v_cvt_pk_bf16_f32 %0, %1, %2" : "=v"(r) : "v"(lo), "v"(hi)); return r; }
;     __device__ __forceinline__ void operator()(const f32x4 (&acc)[2][2][4][2], const Unit& u, int wr, int wc, int fr, int fq) const {
;     ...
;         for (int ai = 0; ai < 2; ++ai)
; #pragma unroll
;             for (int m = 0; m < 4; ++m) {
;                 const int row = row0 + ai * 128 + m * 16; const size_t ro = (size_t)row * DM + col0;
;                 float s = 0.f;
; #pragma unroll
;                 for (int bj = 0; bj < 2; ++bj)
; #pragma unroll
;                     for (int n = 0; n < 2; ++n) {
;                         const size_t o = ro + bj * 128 + n * 16;
;                         const f32x4 xn = *(const f32x4*)(xo + o) + acc[ai][bj][m][n];
;                         *(f32x4*)(xf + o) = xn;
;                         u32x2 w; w.x = pk2(xn[0], xn[1]); w.y = pk2(xn[2], xn[3]); *(u32x2*)(xb + o) = w;
;                         s += (xn[0] * xn[0] + xn[1] * xn[1]) + (xn[2] * xn[2] + xn[3] * xn[3]);
;                     }
;                 s += __shfl_xor(s, 16); s += __shfl_xor(s, 32);
;                 if (fq == 0) ssq[(size_t)row * 16 + u.pn * 4 + wc] = s;
;             }
.LBB0_2180:
	s_or_b64 exec, exec, s[42:43]
	v_or_b32_e32 v112, 16, v138
	s_waitcnt lgkmcnt(0)
	v_ashrrev_i32_e32 v113, 31, v112
	v_lshlrev_b64 v[118:119], 10, v[112:113]
	v_lshl_add_u64 v[122:123], v[118:119], 0, v[136:137]
	v_lshlrev_b64 v[124:125], 2, v[122:123]
	v_lshl_add_u64 v[126:127], s[12:13], 0, v[124:125]
	v_lshl_add_u64 v[122:123], v[122:123], 1, s[22:23]
	v_lshl_add_u64 v[124:125], s[16:17], 0, v[124:125]
	s_waitcnt vmcnt(20)
	v_mov_b64_e32 v[118:119], v[186:187]
	v_mov_b64_e32 v[120:121], v[188:189]
	v_add_u32_e32 v163, 0x90040, v162
	global_load_dwordx4 v[186:189], v163, s[12:13] nt
	v_pk_add_f32 v[110:111], v[110:111], v[120:121]
	v_pk_add_f32 v[108:109], v[108:109], v[118:119]
	global_store_dwordx4 v[124:125], v[108:111], off
	v_cvt_pk_bf16_f32 v118, v108, v109
	v_cvt_pk_bf16_f32 v119, v110, v111
	v_mul_f32_e32 v109, v109, v109
	v_mul_f32_e32 v111, v111, v111
	v_fmac_f32_e32 v109, v108, v108
	v_fmac_f32_e32 v111, v110, v110
	v_add_f32_e32 v108, v109, v111
	s_waitcnt vmcnt(21)
	v_mov_b64_e32 v[118:119], v[190:191]
	v_mov_b64_e32 v[120:121], v[192:193]
	v_add_u32_e32 v163, 0x90200, v162
	global_load_dwordx4 v[190:193], v163, s[12:13] nt
	v_pk_add_f32 v[106:107], v[106:107], v[120:121]
	v_pk_add_f32 v[104:105], v[104:105], v[118:119]
	global_store_dwordx4 v[124:125], v[104:107], off offset:64
	v_cvt_pk_bf16_f32 v118, v104, v105
	v_cvt_pk_bf16_f32 v119, v106, v107
	v_mul_f32_e32 v105, v105, v105
	v_mul_f32_e32 v107, v107, v107
	v_fmac_f32_e32 v105, v104, v104
	v_fmac_f32_e32 v107, v106, v106
	v_add_f32_e32 v104, v105, v107
	v_add_f32_e32 v104, v108, v104
	s_waitcnt vmcnt(22)
	v_mov_b64_e32 v[118:119], v[194:195]
	v_mov_b64_e32 v[120:121], v[196:197]
	v_add_u32_e32 v163, 0x90240, v162
	global_load_dwordx4 v[194:197], v163, s[12:13] nt
	v_pk_add_f32 v[102:103], v[102:103], v[120:121]
	v_pk_add_f32 v[100:101], v[100:101], v[118:119]
	global_store_dwordx4 v[124:125], v[100:103], off offset:512
	v_cvt_pk_bf16_f32 v118, v100, v101
	v_cvt_pk_bf16_f32 v119, v102, v103
	v_mul_f32_e32 v101, v101, v101
	v_mul_f32_e32 v103, v103, v103
	v_fmac_f32_e32 v101, v100, v100
	v_fmac_f32_e32 v103, v102, v102
	v_add_f32_e32 v100, v101, v103
	v_add_f32_e32 v102, v104, v100
	s_waitcnt vmcnt(23)
	v_mov_b64_e32 v[118:119], v[198:199]
	v_mov_b64_e32 v[120:121], v[200:201]
	v_add_u32_e32 v163, 0xa0000, v162
	global_load_dwordx4 v[198:201], v163, s[12:13] nt
	v_pk_add_f32 v[100:101], v[98:99], v[120:121]
	v_pk_add_f32 v[98:99], v[96:97], v[118:119]
	v_mul_f32_e32 v97, v101, v101
	v_mul_f32_e32 v96, v99, v99
	v_fmac_f32_e32 v96, v98, v98
	v_fmac_f32_e32 v97, v100, v100
	v_add_f32_e32 v96, v96, v97
	v_add_f32_e32 v96, v102, v96
	ds_bpermute_b32 v97, v116, v96
	global_store_dwordx4 v[124:125], v[98:101], off offset:576
	s_waitcnt lgkmcnt(0)
	v_add_f32_e32 v96, v96, v97
	ds_bpermute_b32 v97, v114, v96
	v_cvt_pk_bf16_f32 v98, v98, v99
	v_cvt_pk_bf16_f32 v99, v100, v101
	s_and_saveexec_b64 s[42:43], s[8:9]
	s_cbranch_execz .LBB0_2182
	s_waitcnt lgkmcnt(0)
	v_add_f32_e32 v98, v96, v97
	v_lshlrev_b64 v[96:97], 6, v[112:113]
	v_lshl_add_u64 v[96:97], s[24:25], 0, v[96:97]
	v_lshl_add_u64 v[96:97], s[40:41], 2, v[96:97]
	s_lshl_b32 s26, s74, 2
	v_lshl_add_u64 v[96:97], v[96:97], 0, s[26:27]
	global_store_dword v[96:97], v98, off
; __device__ __forceinline__ unsigned pk2(float lo, float hi) { unsigned r; asm volatile("v_cvt_pk_bf16_f32 %0, %1, %2" : "=v"(r) : "v"(lo), "v"(hi)); return r; }
;     __device__ __forceinline__ void operator()(const f32x4 (&acc)[2][2][4][2], const Unit& u, int wr, int wc, int fr, int fq) const {
;     ...
;         for (int ai = 0; ai < 2; ++ai)
; #pragma unroll
;             for (int m = 0; m < 4; ++m) {
;                 const int row = row0 + ai * 128 + m * 16; const size_t ro = (size_t)row * DM + col0;
;                 float s = 0.f;
; #pragma unroll
;                 for (int bj = 0; bj < 2; ++bj)
; #pragma unroll
;                     for (int n = 0; n < 2; ++n) {
;                         const size_t o = ro + bj * 128 + n * 16;
;                         const f32x4 xn = *(const f32x4*)(xo + o) + acc[ai][bj][m][n];
;                         *(f32x4*)(xf + o) = xn;
;                         u32x2 w; w.x = pk2(xn[0], xn[1]); w.y = pk2(xn[2], xn[3]); *(u32x2*)(xb + o) = w;
;                         s += (xn[0] * xn[0] + xn[1] * xn[1]) + (xn[2] * xn[2] + xn[3] * xn[3]);
;                     }
;                 s += __shfl_xor(s, 16); s += __shfl_xor(s, 32);
;                 if (fq == 0) ssq[(size_t)row * 16 + u.pn * 4 + wc] = s;
;             }
.LBB0_2182:
	s_or_b64 exec, exec, s[42:43]
	v_or_b32_e32 v96, 32, v138
	s_waitcnt lgkmcnt(0)
	v_ashrrev_i32_e32 v97, 31, v96
	v_lshlrev_b64 v[98:99], 10, v[96:97]
	v_lshl_add_u64 v[102:103], v[98:99], 0, v[136:137]
	v_lshlrev_b64 v[104:105], 2, v[102:103]
	v_lshl_add_u64 v[106:107], s[12:13], 0, v[104:105]
	v_lshl_add_u64 v[102:103], v[102:103], 1, s[22:23]
	v_lshl_add_u64 v[104:105], s[16:17], 0, v[104:105]
	s_waitcnt vmcnt(24)
	v_mov_b64_e32 v[98:99], v[202:203]
	v_mov_b64_e32 v[100:101], v[204:205]
	v_add_u32_e32 v163, 0xa0040, v162
	global_load_dwordx4 v[202:205], v163, s[12:13] nt
	v_pk_add_f32 v[94:95], v[94:95], v[100:101]
	v_pk_add_f32 v[92:93], v[92:93], v[98:99]
	global_store_dwordx4 v[104:105], v[92:95], off
	v_cvt_pk_bf16_f32 v98, v92, v93
	v_cvt_pk_bf16_f32 v99, v94, v95
	v_mul_f32_e32 v93, v93, v93
	v_mul_f32_e32 v95, v95, v95
	v_fmac_f32_e32 v93, v92, v92
	v_fmac_f32_e32 v95, v94, v94
	v_add_f32_e32 v92, v93, v95
	s_waitcnt vmcnt(25)
	v_mov_b64_e32 v[98:99], v[206:207]
	v_mov_b64_e32 v[100:101], v[208:209]
	v_add_u32_e32 v163, 0xa0200, v162
	global_load_dwordx4 v[206:209], v163, s[12:13] nt
	v_pk_add_f32 v[90:91], v[90:91], v[100:101]
	v_pk_add_f32 v[88:89], v[88:89], v[98:99]
	global_store_dwordx4 v[104:105], v[88:91], off offset:64
	v_cvt_pk_bf16_f32 v98, v88, v89
	v_cvt_pk_bf16_f32 v99, v90, v91
	v_mul_f32_e32 v89, v89, v89
	v_mul_f32_e32 v91, v91, v91
	v_fmac_f32_e32 v89, v88, v88
	v_fmac_f32_e32 v91, v90, v90
	v_add_f32_e32 v88, v89, v91
	v_add_f32_e32 v88, v92, v88
	s_waitcnt vmcnt(26)
	v_mov_b64_e32 v[98:99], v[210:211]
	v_mov_b64_e32 v[100:101], v[212:213]
	v_add_u32_e32 v163, 0xa0240, v162
	global_load_dwordx4 v[210:213], v163, s[12:13] nt
	v_pk_add_f32 v[86:87], v[86:87], v[100:101]
	v_pk_add_f32 v[84:85], v[84:85], v[98:99]
	global_store_dwordx4 v[104:105], v[84:87], off offset:512
	v_cvt_pk_bf16_f32 v98, v84, v85
	v_cvt_pk_bf16_f32 v99, v86, v87
	v_mul_f32_e32 v85, v85, v85
	v_mul_f32_e32 v87, v87, v87
	v_fmac_f32_e32 v85, v84, v84
	v_fmac_f32_e32 v87, v86, v86
	v_add_f32_e32 v84, v85, v87
	v_add_f32_e32 v86, v88, v84
	s_waitcnt vmcnt(27)
	v_mov_b64_e32 v[98:99], v[232:233]
	v_mov_b64_e32 v[100:101], v[234:235]
	v_add_u32_e32 v163, 0xb0000, v162
	global_load_dwordx4 v[232:235], v163, s[12:13] nt
	v_pk_add_f32 v[84:85], v[82:83], v[100:101]
	v_pk_add_f32 v[82:83], v[80:81], v[98:99]
	v_mul_f32_e32 v81, v85, v85
	v_mul_f32_e32 v80, v83, v83
	v_fmac_f32_e32 v80, v82, v82
	v_fmac_f32_e32 v81, v84, v84
	v_add_f32_e32 v80, v80, v81
	v_add_f32_e32 v80, v86, v80
	ds_bpermute_b32 v81, v116, v80
	global_store_dwordx4 v[104:105], v[82:85], off offset:576
	s_waitcnt lgkmcnt(0)
	v_add_f32_e32 v80, v80, v81
	ds_bpermute_b32 v81, v114, v80
	v_cvt_pk_bf16_f32 v82, v82, v83
	v_cvt_pk_bf16_f32 v83, v84, v85
	s_and_saveexec_b64 s[42:43], s[8:9]
	s_cbranch_execz .LBB0_2184
	s_waitcnt lgkmcnt(0)
	v_add_f32_e32 v82, v80, v81
	v_lshlrev_b64 v[80:81], 6, v[96:97]
	v_lshl_add_u64 v[80:81], s[24:25], 0, v[80:81]
	v_lshl_add_u64 v[80:81], s[40:41], 2, v[80:81]
	s_lshl_b32 s26, s74, 2
	v_lshl_add_u64 v[80:81], v[80:81], 0, s[26:27]
	global_store_dword v[80:81], v82, off
.LBB0_2184:
	s_or_b64 exec, exec, s[42:43]
	v_or_b32_e32 v80, 48, v138
	s_waitcnt lgkmcnt(0)
	v_ashrrev_i32_e32 v81, 31, v80
	v_lshlrev_b64 v[82:83], 10, v[80:81]
	v_lshl_add_u64 v[86:87], v[82:83], 0, v[136:137]
	v_lshlrev_b64 v[88:89], 2, v[86:87]
	v_lshl_add_u64 v[90:91], s[12:13], 0, v[88:89]
	v_lshl_add_u64 v[86:87], v[86:87], 1, s[22:23]
	v_lshl_add_u64 v[88:89], s[16:17], 0, v[88:89]
	s_waitcnt vmcnt(28)
	v_mov_b64_e32 v[82:83], v[236:237]
	v_mov_b64_e32 v[84:85], v[238:239]
	v_add_u32_e32 v163, 0xb0040, v162
	global_load_dwordx4 v[236:239], v163, s[12:13] nt
	v_pk_add_f32 v[78:79], v[78:79], v[84:85]
	v_pk_add_f32 v[76:77], v[76:77], v[82:83]
	global_store_dwordx4 v[88:89], v[76:79], off
	v_cvt_pk_bf16_f32 v82, v76, v77
	v_cvt_pk_bf16_f32 v83, v78, v79
	v_mul_f32_e32 v77, v77, v77
	v_mul_f32_e32 v79, v79, v79
	v_fmac_f32_e32 v77, v76, v76
	v_fmac_f32_e32 v79, v78, v78
	v_add_f32_e32 v76, v77, v79
	s_waitcnt vmcnt(29)
	v_mov_b64_e32 v[82:83], v[240:241]
	v_mov_b64_e32 v[84:85], v[242:243]
	v_add_u32_e32 v163, 0xb0200, v162
	global_load_dwordx4 v[240:243], v163, s[12:13] nt
	v_pk_add_f32 v[74:75], v[74:75], v[84:85]
	v_pk_add_f32 v[72:73], v[72:73], v[82:83]
	global_store_dwordx4 v[88:89], v[72:75], off offset:64
	v_cvt_pk_bf16_f32 v82, v72, v73
	v_cvt_pk_bf16_f32 v83, v74, v75
	v_mul_f32_e32 v73, v73, v73
	v_mul_f32_e32 v75, v75, v75
	v_fmac_f32_e32 v73, v72, v72
	v_fmac_f32_e32 v75, v74, v74
	v_add_f32_e32 v72, v73, v75
	v_add_f32_e32 v72, v76, v72
	s_waitcnt vmcnt(30)
	v_mov_b64_e32 v[82:83], v[244:245]
	v_mov_b64_e32 v[84:85], v[246:247]
	v_add_u32_e32 v163, 0xb0240, v162
	global_load_dwordx4 v[244:247], v163, s[12:13] nt
	v_pk_add_f32 v[70:71], v[70:71], v[84:85]
	v_pk_add_f32 v[68:69], v[68:69], v[82:83]
	global_store_dwordx4 v[88:89], v[68:71], off offset:512
	v_cvt_pk_bf16_f32 v82, v68, v69
	v_cvt_pk_bf16_f32 v83, v70, v71
	v_mul_f32_e32 v69, v69, v69
	v_mul_f32_e32 v71, v71, v71
	v_fmac_f32_e32 v69, v68, v68
	v_fmac_f32_e32 v71, v70, v70
	v_add_f32_e32 v68, v69, v71
	v_add_f32_e32 v70, v72, v68
	s_waitcnt vmcnt(31)
	v_mov_b64_e32 v[82:83], v[248:249]
	v_mov_b64_e32 v[84:85], v[250:251]
	v_pk_add_f32 v[68:69], v[66:67], v[84:85]
	v_pk_add_f32 v[66:67], v[64:65], v[82:83]
	v_mul_f32_e32 v65, v69, v69
	v_mul_f32_e32 v64, v67, v67
	v_fmac_f32_e32 v64, v66, v66
	v_fmac_f32_e32 v65, v68, v68
	v_add_f32_e32 v64, v64, v65
	v_add_f32_e32 v64, v70, v64
	ds_bpermute_b32 v65, v116, v64
	global_store_dwordx4 v[88:89], v[66:69], off offset:576
	s_waitcnt lgkmcnt(0)
	v_add_f32_e32 v64, v64, v65
	ds_bpermute_b32 v65, v114, v64
	v_cvt_pk_bf16_f32 v66, v66, v67
	v_cvt_pk_bf16_f32 v67, v68, v69
	s_and_saveexec_b64 s[42:43], s[8:9]
	s_cbranch_execz .LBB0_2186
	s_waitcnt lgkmcnt(0)
	v_add_f32_e32 v66, v64, v65
	v_lshlrev_b64 v[64:65], 6, v[80:81]
	v_lshl_add_u64 v[64:65], s[24:25], 0, v[64:65]
	v_lshl_add_u64 v[64:65], s[40:41], 2, v[64:65]
	s_lshl_b32 s26, s74, 2
	v_lshl_add_u64 v[64:65], v[64:65], 0, s[26:27]
	global_store_dword v[64:65], v66, off
